# 8-byte epilogue tile stores widened to 16-byte via v_permlane16_swap_b32 in P1 (U, Q/K, gate epilogues), P3 2nd epilogue, P4, P5: store instruction count halved, same bytes/values; vmcnt waits re-deri
# speedup vs baseline: 1.0379x; 1.0201x over previous
.LBB0_155:
	s_or_b64 exec, exec, s[8:9]
	v_lshl_or_b32 v168, s96, 8, v163
	v_mov_b32_e32 v166, v1
	s_cmp_gt_i32 s94, 1
	s_mov_b64 s[8:9], -1
	s_waitcnt vmcnt(0)
	s_barrier
	s_cbranch_scc0 .LBB0_181
	s_cmp_gt_u32 s94, 3
	s_cbranch_scc0 .LBB0_162
	s_cmp_gt_u32 s94, 11
	s_cbranch_scc0 .LBB0_159
	v_mbcnt_lo_u32_b32 v244, -1, 0
	v_mbcnt_hi_u32_b32 v244, -1, v244
	v_bfe_u32 v244, v244, 4, 1
	v_mul_u32_u24_e32 v244, 24, v244
	v_mov_b32_e32 v245, 0
	s_lshl_b32 s0, s94, 8
	s_add_i32 s8, s0, 0xfffff000
	s_ashr_i32 s9, s8, 31
	v_readlane_b32 s52, v249, 38
	s_lshl_b64 s[14:15], s[8:9], 2
	v_readlane_b32 s58, v249, 44
	v_readlane_b32 s59, v249, 45
	s_add_u32 s14, s58, s14
	s_addc_u32 s15, s59, s15
	v_ashrrev_i32_e32 v167, 31, v166
	v_lshl_add_u64 v[130:131], v[166:167], 2, s[14:15]
	global_load_dwordx4 v[158:161], v[130:131], off
	global_load_dwordx4 v[154:157], v[130:131], off offset:64
	global_load_dwordx4 v[150:153], v[130:131], off offset:128
	global_load_dwordx4 v[146:149], v[130:131], off offset:192
	global_load_dwordx4 v[142:145], v[130:131], off offset:512
	global_load_dwordx4 v[138:141], v[130:131], off offset:576
	global_load_dwordx4 v[134:137], v[130:131], off offset:640
	s_nop 0
	global_load_dwordx4 v[130:133], v[130:131], off offset:704
	v_ashrrev_i32_e32 v169, 31, v168
	v_lshlrev_b64 v[170:171], 12, v[168:169]
	v_lshl_add_u64 v[170:171], s[76:77], 0, v[170:171]
	v_lshl_add_u64 v[170:171], s[8:9], 1, v[170:171]
	v_lshl_add_u64 v[170:171], v[166:167], 1, v[170:171]
	s_mov_b64 s[0:1], 0x10000
	v_readlane_b32 s53, v249, 39
	v_readlane_b32 s54, v249, 40
	v_readlane_b32 s55, v249, 41
	v_readlane_b32 s56, v249, 42
	v_readlane_b32 s57, v249, 43
	v_readlane_b32 s60, v249, 46
	v_readlane_b32 s61, v249, 47
	v_readlane_b32 s62, v249, 48
	v_readlane_b32 s63, v249, 49
	v_readlane_b32 s64, v249, 50
	v_readlane_b32 s65, v249, 51
	v_readlane_b32 s66, v249, 52
	v_readlane_b32 s67, v249, 53
	s_mov_b64 s[8:9], 0
	s_waitcnt vmcnt(7)
	v_add_f32_e32 v172, v128, v160
	v_mul_f32_e32 v172, 0xbfb8aa3b, v172
	v_exp_f32_e32 v172, v172
	v_add_f32_e32 v164, v126, v158
	v_add_f32_e32 v169, v127, v159
	v_mul_f32_e32 v164, 0xbfb8aa3b, v164
	v_add_f32_e32 v172, 1.0, v172
	v_rcp_f32_e32 v173, v172
	v_add_f32_e32 v172, v129, v161
	v_mul_f32_e32 v169, 0xbfb8aa3b, v169
	v_mul_f32_e32 v172, 0xbfb8aa3b, v172
	v_exp_f32_e32 v164, v164
	v_exp_f32_e32 v169, v169
	v_exp_f32_e32 v172, v172
	s_waitcnt vmcnt(6)
	v_add_f32_e32 v167, v123, v155
	v_add_f32_e32 v164, 1.0, v164
	v_add_f32_e32 v169, 1.0, v169
	v_add_f32_e32 v172, 1.0, v172
	v_rcp_f32_e32 v164, v164
	v_rcp_f32_e32 v169, v169
	v_rcp_f32_e32 v174, v172
	v_mul_f32_e32 v167, 0xbfb8aa3b, v167
	v_exp_f32_e32 v167, v167
	v_cvt_pk_bf16_f32 v224, v164, v169
	v_cvt_pk_bf16_f32 v225, v173, v174
	v_add_f32_e32 v164, v122, v154
	v_add_f32_e32 v169, v124, v156
	v_add_f32_e32 v172, v125, v157
	v_mul_f32_e32 v164, 0xbfb8aa3b, v164
	v_mul_f32_e32 v169, 0xbfb8aa3b, v169
	v_mul_f32_e32 v172, 0xbfb8aa3b, v172
	v_exp_f32_e32 v164, v164
	v_exp_f32_e32 v169, v169
	v_exp_f32_e32 v172, v172
	v_add_f32_e32 v167, 1.0, v167
	v_add_f32_e32 v164, 1.0, v164
	v_add_f32_e32 v169, 1.0, v169
	v_add_f32_e32 v172, 1.0, v172
	v_rcp_f32_e32 v164, v164
	v_rcp_f32_e32 v167, v167
	v_rcp_f32_e32 v169, v169
	v_rcp_f32_e32 v173, v172
	v_cvt_pk_bf16_f32 v226, v164, v167
	s_waitcnt vmcnt(5)
	v_add_f32_e32 v164, v118, v150
	v_cvt_pk_bf16_f32 v227, v169, v173
	v_add_f32_e32 v167, v119, v151
	v_add_f32_e32 v169, v120, v152
	v_add_f32_e32 v172, v121, v153
	v_mul_f32_e32 v164, 0xbfb8aa3b, v164
	v_mul_f32_e32 v167, 0xbfb8aa3b, v167
	v_mul_f32_e32 v169, 0xbfb8aa3b, v169
	v_mul_f32_e32 v172, 0xbfb8aa3b, v172
	v_exp_f32_e32 v164, v164
	v_exp_f32_e32 v167, v167
	v_exp_f32_e32 v169, v169
	v_exp_f32_e32 v172, v172
	v_add_f32_e32 v164, 1.0, v164
	v_add_f32_e32 v167, 1.0, v167
	v_add_f32_e32 v169, 1.0, v169
	v_add_f32_e32 v172, 1.0, v172
	v_rcp_f32_e32 v164, v164
	v_rcp_f32_e32 v167, v167
	v_rcp_f32_e32 v169, v169
	v_rcp_f32_e32 v173, v172
	v_cvt_pk_bf16_f32 v228, v164, v167
	s_waitcnt vmcnt(4)
	v_add_f32_e32 v164, v114, v146
	v_cvt_pk_bf16_f32 v229, v169, v173
	v_add_f32_e32 v167, v115, v147
	v_add_f32_e32 v169, v116, v148
	v_add_f32_e32 v172, v117, v149
	v_mul_f32_e32 v164, 0xbfb8aa3b, v164
	v_mul_f32_e32 v167, 0xbfb8aa3b, v167
	v_mul_f32_e32 v169, 0xbfb8aa3b, v169
	v_mul_f32_e32 v172, 0xbfb8aa3b, v172
	v_exp_f32_e32 v164, v164
	v_exp_f32_e32 v167, v167
	v_exp_f32_e32 v169, v169
	v_exp_f32_e32 v172, v172
	v_add_f32_e32 v164, 1.0, v164
	v_add_f32_e32 v167, 1.0, v167
	v_add_f32_e32 v169, 1.0, v169
	v_add_f32_e32 v172, 1.0, v172
	v_rcp_f32_e32 v164, v164
	v_rcp_f32_e32 v167, v167
	v_rcp_f32_e32 v169, v169
	v_rcp_f32_e32 v173, v172
	v_cvt_pk_bf16_f32 v230, v164, v167
	s_waitcnt vmcnt(3)
	v_add_f32_e32 v164, v110, v142
	v_cvt_pk_bf16_f32 v231, v169, v173
	s_nop 1
	v_permlane16_swap_b32_e32 v224, v226
	v_permlane16_swap_b32_e32 v225, v227
	v_permlane16_swap_b32_e32 v228, v230
	v_permlane16_swap_b32_e32 v229, v231
	v_lshl_add_u64 v[240:241], v[170:171], 0, v[244:245]
	global_store_dwordx4 v[240:241], v[224:227], off
	global_store_dwordx4 v[240:241], v[228:231], off offset:64
	v_add_f32_e32 v167, v111, v143
	v_add_f32_e32 v169, v112, v144
	v_add_f32_e32 v172, v113, v145
	v_mul_f32_e32 v164, 0xbfb8aa3b, v164
	v_mul_f32_e32 v167, 0xbfb8aa3b, v167
	v_mul_f32_e32 v169, 0xbfb8aa3b, v169
	v_mul_f32_e32 v172, 0xbfb8aa3b, v172
	v_exp_f32_e32 v164, v164
	v_exp_f32_e32 v167, v167
	v_exp_f32_e32 v169, v169
	v_exp_f32_e32 v172, v172
	v_add_f32_e32 v164, 1.0, v164
	v_add_f32_e32 v167, 1.0, v167
	v_add_f32_e32 v169, 1.0, v169
	v_add_f32_e32 v172, 1.0, v172
	v_rcp_f32_e32 v164, v164
	v_rcp_f32_e32 v167, v167
	v_rcp_f32_e32 v169, v169
	v_rcp_f32_e32 v173, v172
	v_cvt_pk_bf16_f32 v232, v164, v167
	s_waitcnt vmcnt(4)
	v_add_f32_e32 v164, v106, v138
	v_cvt_pk_bf16_f32 v233, v169, v173
	v_add_f32_e32 v167, v107, v139
	v_add_f32_e32 v169, v108, v140
	v_add_f32_e32 v172, v109, v141
	v_mul_f32_e32 v164, 0xbfb8aa3b, v164
	v_mul_f32_e32 v167, 0xbfb8aa3b, v167
	v_mul_f32_e32 v169, 0xbfb8aa3b, v169
	v_mul_f32_e32 v172, 0xbfb8aa3b, v172
	v_exp_f32_e32 v164, v164
	v_exp_f32_e32 v167, v167
	v_exp_f32_e32 v169, v169
	v_exp_f32_e32 v172, v172
	v_add_f32_e32 v164, 1.0, v164
	v_add_f32_e32 v167, 1.0, v167
	v_add_f32_e32 v169, 1.0, v169
	v_add_f32_e32 v172, 1.0, v172
	v_rcp_f32_e32 v164, v164
	v_rcp_f32_e32 v167, v167
	v_rcp_f32_e32 v169, v169
	v_rcp_f32_e32 v173, v172
	v_cvt_pk_bf16_f32 v234, v164, v167
	s_waitcnt vmcnt(3)
	v_add_f32_e32 v164, v102, v134
	v_cvt_pk_bf16_f32 v235, v169, v173
	v_add_f32_e32 v167, v103, v135
	v_add_f32_e32 v169, v104, v136
	v_add_f32_e32 v172, v105, v137
	v_mul_f32_e32 v164, 0xbfb8aa3b, v164
	v_mul_f32_e32 v167, 0xbfb8aa3b, v167
	v_mul_f32_e32 v169, 0xbfb8aa3b, v169
	v_mul_f32_e32 v172, 0xbfb8aa3b, v172
	v_exp_f32_e32 v164, v164
	v_exp_f32_e32 v167, v167
	v_exp_f32_e32 v169, v169
	v_exp_f32_e32 v172, v172
	v_add_f32_e32 v164, 1.0, v164
	v_add_f32_e32 v167, 1.0, v167
	v_add_f32_e32 v169, 1.0, v169
	v_add_f32_e32 v172, 1.0, v172
	v_rcp_f32_e32 v164, v164
	v_rcp_f32_e32 v167, v167
	v_rcp_f32_e32 v169, v169
	v_rcp_f32_e32 v173, v172
	v_cvt_pk_bf16_f32 v236, v164, v167
	s_waitcnt vmcnt(2)
	v_add_f32_e32 v164, v98, v130
	v_cvt_pk_bf16_f32 v237, v169, v173
	v_add_f32_e32 v167, v99, v131
	v_add_f32_e32 v169, v100, v132
	v_add_f32_e32 v172, v101, v133
	v_mul_f32_e32 v164, 0xbfb8aa3b, v164
	v_mul_f32_e32 v167, 0xbfb8aa3b, v167
	v_mul_f32_e32 v169, 0xbfb8aa3b, v169
	v_mul_f32_e32 v172, 0xbfb8aa3b, v172
	v_exp_f32_e32 v164, v164
	v_exp_f32_e32 v167, v167
	v_exp_f32_e32 v169, v169
	v_exp_f32_e32 v172, v172
	v_add_f32_e32 v164, 1.0, v164
	v_add_f32_e32 v167, 1.0, v167
	v_add_f32_e32 v169, 1.0, v169
	v_add_f32_e32 v172, 1.0, v172
	v_rcp_f32_e32 v164, v164
	v_rcp_f32_e32 v167, v167
	v_rcp_f32_e32 v169, v169
	v_rcp_f32_e32 v173, v172
	v_cvt_pk_bf16_f32 v238, v164, v167
	v_add_f32_e32 v164, v94, v158
	v_cvt_pk_bf16_f32 v239, v169, v173
	s_nop 1
	v_permlane16_swap_b32_e32 v232, v234
	v_permlane16_swap_b32_e32 v233, v235
	v_permlane16_swap_b32_e32 v236, v238
	v_permlane16_swap_b32_e32 v237, v239
	v_lshl_add_u64 v[240:241], v[170:171], 0, v[244:245]
	global_store_dwordx4 v[240:241], v[232:235], off offset:256
	global_store_dwordx4 v[240:241], v[236:239], off offset:320
	v_add_f32_e32 v169, v96, v160
	v_add_f32_e32 v172, v97, v161
	v_mul_f32_e32 v169, 0xbfb8aa3b, v169
	v_mul_f32_e32 v172, 0xbfb8aa3b, v172
	v_add_f32_e32 v167, v95, v159
	v_exp_f32_e32 v169, v169
	v_exp_f32_e32 v172, v172
	v_mul_f32_e32 v164, 0xbfb8aa3b, v164
	v_mul_f32_e32 v167, 0xbfb8aa3b, v167
	v_exp_f32_e32 v164, v164
	v_exp_f32_e32 v167, v167
	v_add_f32_e32 v169, 1.0, v169
	v_add_f32_e32 v172, 1.0, v172
	v_rcp_f32_e32 v169, v169
	v_rcp_f32_e32 v172, v172
	v_add_f32_e32 v164, 1.0, v164
	v_add_f32_e32 v167, 1.0, v167
	v_rcp_f32_e32 v164, v164
	v_rcp_f32_e32 v167, v167
	v_cvt_pk_bf16_f32 v179, v169, v172
	v_lshl_add_u64 v[172:173], v[170:171], 0, s[0:1]
	s_mov_b32 s0, 0x10000
	v_add_co_u32_e32 v176, vcc, s0, v170
	v_cvt_pk_bf16_f32 v178, v164, v167
	s_nop 0
	v_addc_co_u32_e32 v177, vcc, 0, v171, vcc
	v_add_f32_e32 v164, v90, v154
	v_add_f32_e32 v167, v91, v155
	v_add_f32_e32 v169, v92, v156
	v_add_f32_e32 v174, v93, v157
	v_mul_f32_e32 v164, 0xbfb8aa3b, v164
	v_mul_f32_e32 v167, 0xbfb8aa3b, v167
	v_mul_f32_e32 v169, 0xbfb8aa3b, v169
	v_mul_f32_e32 v174, 0xbfb8aa3b, v174
	v_exp_f32_e32 v164, v164
	v_exp_f32_e32 v167, v167
	v_exp_f32_e32 v169, v169
	v_exp_f32_e32 v174, v174
	v_add_f32_e32 v164, 1.0, v164
	v_add_f32_e32 v167, 1.0, v167
	v_add_f32_e32 v169, 1.0, v169
	v_add_f32_e32 v174, 1.0, v174
	v_rcp_f32_e32 v164, v164
	v_rcp_f32_e32 v167, v167
	v_rcp_f32_e32 v169, v169
	v_rcp_f32_e32 v175, v174
	s_mov_b64 s[0:1], 0x80000
	v_cvt_pk_bf16_f32 v180, v164, v167
	v_add_f32_e32 v164, v86, v150
	v_cvt_pk_bf16_f32 v181, v169, v175
	v_add_f32_e32 v167, v87, v151
	v_add_f32_e32 v169, v88, v152
	v_add_f32_e32 v174, v89, v153
	v_mul_f32_e32 v164, 0xbfb8aa3b, v164
	v_mul_f32_e32 v167, 0xbfb8aa3b, v167
	v_mul_f32_e32 v169, 0xbfb8aa3b, v169
	v_mul_f32_e32 v174, 0xbfb8aa3b, v174
	v_exp_f32_e32 v164, v164
	v_exp_f32_e32 v167, v167
	v_exp_f32_e32 v169, v169
	v_exp_f32_e32 v174, v174
	v_add_f32_e32 v164, 1.0, v164
	v_add_f32_e32 v167, 1.0, v167
	v_add_f32_e32 v169, 1.0, v169
	v_add_f32_e32 v174, 1.0, v174
	v_rcp_f32_e32 v164, v164
	v_rcp_f32_e32 v167, v167
	v_rcp_f32_e32 v169, v169
	v_rcp_f32_e32 v175, v174
	v_cvt_pk_bf16_f32 v182, v164, v167
	v_add_f32_e32 v164, v82, v146
	v_cvt_pk_bf16_f32 v183, v169, v175
	v_add_f32_e32 v167, v83, v147
	v_add_f32_e32 v169, v84, v148
	v_add_f32_e32 v174, v85, v149
	v_mul_f32_e32 v164, 0xbfb8aa3b, v164
	v_mul_f32_e32 v167, 0xbfb8aa3b, v167
	v_mul_f32_e32 v169, 0xbfb8aa3b, v169
	v_mul_f32_e32 v174, 0xbfb8aa3b, v174
	v_exp_f32_e32 v164, v164
	v_exp_f32_e32 v167, v167
	v_exp_f32_e32 v169, v169
	v_exp_f32_e32 v174, v174
	v_add_f32_e32 v164, 1.0, v164
	v_add_f32_e32 v167, 1.0, v167
	v_add_f32_e32 v169, 1.0, v169
	v_add_f32_e32 v174, 1.0, v174
	v_rcp_f32_e32 v164, v164
	v_rcp_f32_e32 v167, v167
	v_rcp_f32_e32 v169, v169
	v_rcp_f32_e32 v175, v174
	v_cvt_pk_bf16_f32 v184, v164, v167
	v_add_f32_e32 v164, v78, v142
	v_cvt_pk_bf16_f32 v185, v169, v175
	s_nop 1
	v_permlane16_swap_b32_e32 v178, v180
	v_permlane16_swap_b32_e32 v179, v181
	v_permlane16_swap_b32_e32 v182, v184
	v_permlane16_swap_b32_e32 v183, v185
	v_lshl_add_u64 v[240:241], v[172:173], 0, v[244:245]
	global_store_dwordx4 v[240:241], v[178:181], off
	global_store_dwordx4 v[240:241], v[182:185], off offset:64
	v_add_f32_e32 v167, v79, v143
	v_add_f32_e32 v169, v80, v144
	v_add_f32_e32 v174, v81, v145
	v_mul_f32_e32 v164, 0xbfb8aa3b, v164
	v_mul_f32_e32 v167, 0xbfb8aa3b, v167
	v_mul_f32_e32 v169, 0xbfb8aa3b, v169
	v_mul_f32_e32 v174, 0xbfb8aa3b, v174
	v_exp_f32_e32 v164, v164
	v_exp_f32_e32 v167, v167
	v_exp_f32_e32 v169, v169
	v_exp_f32_e32 v174, v174
	v_add_f32_e32 v164, 1.0, v164
	v_add_f32_e32 v167, 1.0, v167
	v_add_f32_e32 v169, 1.0, v169
	v_add_f32_e32 v174, 1.0, v174
	v_rcp_f32_e32 v164, v164
	v_rcp_f32_e32 v167, v167
	v_rcp_f32_e32 v169, v169
	v_rcp_f32_e32 v175, v174
	v_cvt_pk_bf16_f32 v186, v164, v167
	v_add_f32_e32 v164, v74, v138
	v_cvt_pk_bf16_f32 v187, v169, v175
	v_add_f32_e32 v167, v75, v139
	v_add_f32_e32 v169, v76, v140
	v_add_f32_e32 v174, v77, v141
	v_mul_f32_e32 v164, 0xbfb8aa3b, v164
	v_mul_f32_e32 v167, 0xbfb8aa3b, v167
	v_mul_f32_e32 v169, 0xbfb8aa3b, v169
	v_mul_f32_e32 v174, 0xbfb8aa3b, v174
	v_exp_f32_e32 v164, v164
	v_exp_f32_e32 v167, v167
	v_exp_f32_e32 v169, v169
	v_exp_f32_e32 v174, v174
	v_add_f32_e32 v164, 1.0, v164
	v_add_f32_e32 v167, 1.0, v167
	v_add_f32_e32 v169, 1.0, v169
	v_add_f32_e32 v174, 1.0, v174
	v_rcp_f32_e32 v164, v164
	v_rcp_f32_e32 v167, v167
	v_rcp_f32_e32 v169, v169
	v_rcp_f32_e32 v175, v174
	v_cvt_pk_bf16_f32 v188, v164, v167
	v_add_f32_e32 v164, v70, v134
	v_cvt_pk_bf16_f32 v189, v169, v175
	v_add_f32_e32 v167, v71, v135
	v_add_f32_e32 v169, v72, v136
	v_add_f32_e32 v174, v73, v137
	v_mul_f32_e32 v164, 0xbfb8aa3b, v164
	v_mul_f32_e32 v167, 0xbfb8aa3b, v167
	v_mul_f32_e32 v169, 0xbfb8aa3b, v169
	v_mul_f32_e32 v174, 0xbfb8aa3b, v174
	v_exp_f32_e32 v164, v164
	v_exp_f32_e32 v167, v167
	v_exp_f32_e32 v169, v169
	v_exp_f32_e32 v174, v174
	v_add_f32_e32 v164, 1.0, v164
	v_add_f32_e32 v167, 1.0, v167
	v_add_f32_e32 v169, 1.0, v169
	v_add_f32_e32 v174, 1.0, v174
	v_rcp_f32_e32 v164, v164
	v_rcp_f32_e32 v167, v167
	v_rcp_f32_e32 v169, v169
	v_rcp_f32_e32 v175, v174
	v_cvt_pk_bf16_f32 v190, v164, v167
	v_add_f32_e32 v164, v66, v130
	v_cvt_pk_bf16_f32 v191, v169, v175
	v_add_f32_e32 v167, v67, v131
	v_add_f32_e32 v169, v68, v132
	v_add_f32_e32 v174, v69, v133
	v_mul_f32_e32 v164, 0xbfb8aa3b, v164
	v_mul_f32_e32 v167, 0xbfb8aa3b, v167
	v_mul_f32_e32 v169, 0xbfb8aa3b, v169
	v_mul_f32_e32 v174, 0xbfb8aa3b, v174
	v_exp_f32_e32 v164, v164
	v_exp_f32_e32 v167, v167
	v_exp_f32_e32 v169, v169
	v_exp_f32_e32 v174, v174
	v_add_f32_e32 v164, 1.0, v164
	v_add_f32_e32 v167, 1.0, v167
	v_add_f32_e32 v169, 1.0, v169
	v_add_f32_e32 v174, 1.0, v174
	v_rcp_f32_e32 v164, v164
	v_rcp_f32_e32 v167, v167
	v_rcp_f32_e32 v169, v169
	v_rcp_f32_e32 v175, v174
	v_cvt_pk_bf16_f32 v192, v164, v167
	v_add_f32_e32 v164, v62, v158
	v_cvt_pk_bf16_f32 v193, v169, v175
	s_nop 1
	v_permlane16_swap_b32_e32 v186, v188
	v_permlane16_swap_b32_e32 v187, v189
	v_permlane16_swap_b32_e32 v190, v192
	v_permlane16_swap_b32_e32 v191, v193
	v_lshl_add_u64 v[240:241], v[172:173], 0, v[244:245]
	global_store_dwordx4 v[240:241], v[186:189], off offset:256
	global_store_dwordx4 v[240:241], v[190:193], off offset:320
	v_add_f32_e32 v169, v64, v160
	v_add_f32_e32 v172, v65, v161
	v_mul_f32_e32 v169, 0xbfb8aa3b, v169
	v_mul_f32_e32 v172, 0xbfb8aa3b, v172
	v_add_f32_e32 v167, v63, v159
	v_exp_f32_e32 v169, v169
	v_exp_f32_e32 v172, v172
	v_mul_f32_e32 v164, 0xbfb8aa3b, v164
	v_mul_f32_e32 v167, 0xbfb8aa3b, v167
	v_exp_f32_e32 v164, v164
	v_exp_f32_e32 v167, v167
	v_add_f32_e32 v169, 1.0, v169
	v_add_f32_e32 v172, 1.0, v172
	v_rcp_f32_e32 v169, v169
	v_rcp_f32_e32 v172, v172
	v_add_f32_e32 v164, 1.0, v164
	v_add_f32_e32 v167, 1.0, v167
	v_rcp_f32_e32 v164, v164
	v_rcp_f32_e32 v167, v167
	v_cvt_pk_bf16_f32 v195, v169, v172
	v_lshl_add_u64 v[172:173], v[170:171], 0, s[0:1]
	s_mov_b32 s0, 0x80000
	v_add_co_u32_e32 v176, vcc, s0, v170
	v_cvt_pk_bf16_f32 v194, v164, v167
	s_nop 0
	v_addc_co_u32_e32 v177, vcc, 0, v171, vcc
	v_add_f32_e32 v164, v58, v154
	v_add_f32_e32 v167, v59, v155
	v_add_f32_e32 v169, v60, v156
	v_add_f32_e32 v174, v61, v157
	v_mul_f32_e32 v164, 0xbfb8aa3b, v164
	v_mul_f32_e32 v167, 0xbfb8aa3b, v167
	v_mul_f32_e32 v169, 0xbfb8aa3b, v169
	v_mul_f32_e32 v174, 0xbfb8aa3b, v174
	v_exp_f32_e32 v164, v164
	v_exp_f32_e32 v167, v167
	v_exp_f32_e32 v169, v169
	v_exp_f32_e32 v174, v174
	v_add_f32_e32 v164, 1.0, v164
	v_add_f32_e32 v167, 1.0, v167
	v_add_f32_e32 v169, 1.0, v169
	v_add_f32_e32 v174, 1.0, v174
	v_rcp_f32_e32 v164, v164
	v_rcp_f32_e32 v167, v167
	v_rcp_f32_e32 v169, v169
	v_rcp_f32_e32 v175, v174
	v_add_f32_e32 v160, v32, v160
	v_cvt_pk_bf16_f32 v196, v164, v167
	v_add_f32_e32 v164, v54, v150
	v_cvt_pk_bf16_f32 v197, v169, v175
	v_add_f32_e32 v167, v55, v151
	v_add_f32_e32 v169, v56, v152
	v_add_f32_e32 v174, v57, v153
	v_mul_f32_e32 v164, 0xbfb8aa3b, v164
	v_mul_f32_e32 v167, 0xbfb8aa3b, v167
	v_mul_f32_e32 v169, 0xbfb8aa3b, v169
	v_mul_f32_e32 v174, 0xbfb8aa3b, v174
	v_exp_f32_e32 v164, v164
	v_exp_f32_e32 v167, v167
	v_exp_f32_e32 v169, v169
	v_exp_f32_e32 v174, v174
	v_add_f32_e32 v164, 1.0, v164
	v_add_f32_e32 v167, 1.0, v167
	v_add_f32_e32 v169, 1.0, v169
	v_add_f32_e32 v174, 1.0, v174
	v_rcp_f32_e32 v164, v164
	v_rcp_f32_e32 v167, v167
	v_rcp_f32_e32 v169, v169
	v_rcp_f32_e32 v175, v174
	v_mul_f32_e32 v160, 0xbfb8aa3b, v160
	v_cvt_pk_bf16_f32 v198, v164, v167
	v_add_f32_e32 v164, v50, v146
	v_cvt_pk_bf16_f32 v199, v169, v175
	v_add_f32_e32 v167, v51, v147
	v_add_f32_e32 v169, v52, v148
	v_add_f32_e32 v174, v53, v149
	v_mul_f32_e32 v164, 0xbfb8aa3b, v164
	v_mul_f32_e32 v167, 0xbfb8aa3b, v167
	v_mul_f32_e32 v169, 0xbfb8aa3b, v169
	v_mul_f32_e32 v174, 0xbfb8aa3b, v174
	v_exp_f32_e32 v164, v164
	v_exp_f32_e32 v167, v167
	v_exp_f32_e32 v169, v169
	v_exp_f32_e32 v174, v174
	v_add_f32_e32 v164, 1.0, v164
	v_add_f32_e32 v167, 1.0, v167
	v_add_f32_e32 v169, 1.0, v169
	v_add_f32_e32 v174, 1.0, v174
	v_rcp_f32_e32 v164, v164
	v_rcp_f32_e32 v167, v167
	v_rcp_f32_e32 v169, v169
	v_rcp_f32_e32 v175, v174
	v_exp_f32_e32 v160, v160
	v_cvt_pk_bf16_f32 v200, v164, v167
	v_add_f32_e32 v164, v46, v142
	v_cvt_pk_bf16_f32 v201, v169, v175
	v_add_f32_e32 v167, v47, v143
	s_nop 1
	v_permlane16_swap_b32_e32 v194, v196
	v_permlane16_swap_b32_e32 v195, v197
	v_permlane16_swap_b32_e32 v198, v200
	v_permlane16_swap_b32_e32 v199, v201
	v_lshl_add_u64 v[240:241], v[172:173], 0, v[244:245]
	global_store_dwordx4 v[240:241], v[194:197], off
	global_store_dwordx4 v[240:241], v[198:201], off offset:64
	v_mul_f32_e32 v164, 0xbfb8aa3b, v164
	v_mul_f32_e32 v167, 0xbfb8aa3b, v167
	v_add_f32_e32 v169, v48, v144
	v_add_f32_e32 v174, v49, v145
	v_exp_f32_e32 v164, v164
	v_exp_f32_e32 v167, v167
	v_mul_f32_e32 v169, 0xbfb8aa3b, v169
	v_mul_f32_e32 v174, 0xbfb8aa3b, v174
	v_exp_f32_e32 v169, v169
	v_exp_f32_e32 v174, v174
	v_add_f32_e32 v164, 1.0, v164
	v_add_f32_e32 v167, 1.0, v167
	v_rcp_f32_e32 v164, v164
	v_rcp_f32_e32 v167, v167
	v_add_f32_e32 v169, 1.0, v169
	v_add_f32_e32 v174, 1.0, v174
	v_rcp_f32_e32 v169, v169
	v_rcp_f32_e32 v175, v174
	v_cvt_pk_bf16_f32 v224, v164, v167
	v_add_f32_e32 v164, v42, v138
	v_add_f32_e32 v167, v43, v139
	v_cvt_pk_bf16_f32 v225, v169, v175
	v_mul_f32_e32 v164, 0xbfb8aa3b, v164
	v_mul_f32_e32 v167, 0xbfb8aa3b, v167
	v_exp_f32_e32 v164, v164
	v_exp_f32_e32 v167, v167
	v_add_f32_e32 v169, v44, v140
	v_add_f32_e32 v174, v45, v141
	v_mul_f32_e32 v169, 0xbfb8aa3b, v169
	v_mul_f32_e32 v174, 0xbfb8aa3b, v174
	v_exp_f32_e32 v169, v169
	v_exp_f32_e32 v174, v174
	v_add_f32_e32 v164, 1.0, v164
	v_add_f32_e32 v167, 1.0, v167
	v_rcp_f32_e32 v164, v164
	v_rcp_f32_e32 v167, v167
	v_add_f32_e32 v169, 1.0, v169
	v_add_f32_e32 v174, 1.0, v174
	v_rcp_f32_e32 v169, v169
	v_rcp_f32_e32 v175, v174
	v_cvt_pk_bf16_f32 v226, v164, v167
	v_add_f32_e32 v164, v38, v134
	v_add_f32_e32 v167, v39, v135
	v_mul_f32_e32 v164, 0xbfb8aa3b, v164
	v_mul_f32_e32 v167, 0xbfb8aa3b, v167
	v_cvt_pk_bf16_f32 v227, v169, v175
	v_exp_f32_e32 v164, v164
	v_exp_f32_e32 v167, v167
	v_add_f32_e32 v169, v40, v136
	v_add_f32_e32 v174, v41, v137
	v_mul_f32_e32 v169, 0xbfb8aa3b, v169
	v_mul_f32_e32 v174, 0xbfb8aa3b, v174
	v_exp_f32_e32 v169, v169
	v_exp_f32_e32 v174, v174
	v_add_f32_e32 v164, 1.0, v164
	v_add_f32_e32 v167, 1.0, v167
	v_rcp_f32_e32 v164, v164
	v_rcp_f32_e32 v167, v167
	v_add_f32_e32 v169, 1.0, v169
	v_add_f32_e32 v174, 1.0, v174
	v_rcp_f32_e32 v169, v169
	v_rcp_f32_e32 v175, v174
	v_cvt_pk_bf16_f32 v228, v164, v167
	v_add_f32_e32 v164, v34, v130
	v_add_f32_e32 v167, v35, v131
	v_mul_f32_e32 v164, 0xbfb8aa3b, v164
	v_mul_f32_e32 v167, 0xbfb8aa3b, v167
	v_exp_f32_e32 v164, v164
	v_exp_f32_e32 v167, v167
	v_cvt_pk_bf16_f32 v229, v169, v175
	v_add_f32_e32 v174, v37, v133
	v_mul_f32_e32 v174, 0xbfb8aa3b, v174
	v_add_f32_e32 v164, 1.0, v164
	v_add_f32_e32 v167, 1.0, v167
	v_exp_f32_e32 v174, v174
	v_rcp_f32_e32 v164, v164
	v_rcp_f32_e32 v167, v167
	v_add_f32_e32 v158, v30, v158
	v_add_f32_e32 v159, v31, v159
	v_add_f32_e32 v174, 1.0, v174
	v_mul_f32_e32 v158, 0xbfb8aa3b, v158
	v_mul_f32_e32 v159, 0xbfb8aa3b, v159
	v_add_f32_e32 v160, 1.0, v160
	v_add_f32_e32 v169, v36, v132
	v_rcp_f32_e32 v175, v174
	v_cvt_pk_bf16_f32 v230, v164, v167
	v_exp_f32_e32 v158, v158
	v_exp_f32_e32 v159, v159
	v_rcp_f32_e32 v164, v160
	v_add_f32_e32 v160, v33, v161
	v_add_f32_e32 v154, v26, v154
	v_add_f32_e32 v155, v27, v155
	v_add_f32_e32 v156, v28, v156
	v_add_f32_e32 v157, v29, v157
	v_add_f32_e32 v150, v22, v150
	v_add_f32_e32 v151, v23, v151
	v_add_f32_e32 v152, v24, v152
	v_add_f32_e32 v153, v25, v153
	v_add_f32_e32 v146, v18, v146
	v_add_f32_e32 v147, v19, v147
	v_add_f32_e32 v148, v20, v148
	v_add_f32_e32 v149, v21, v149
	v_add_f32_e32 v142, v14, v142
	v_add_f32_e32 v143, v15, v143
	v_add_f32_e32 v144, v16, v144
	v_add_f32_e32 v145, v17, v145
	v_add_f32_e32 v138, v10, v138
	v_add_f32_e32 v139, v11, v139
	v_add_f32_e32 v140, v12, v140
	v_add_f32_e32 v141, v13, v141
	v_add_f32_e32 v134, v6, v134
	v_add_f32_e32 v135, v7, v135
	v_add_f32_e32 v136, v8, v136
	v_add_f32_e32 v137, v9, v137
	v_add_f32_e32 v130, v2, v130
	v_add_f32_e32 v131, v3, v131
	v_add_f32_e32 v132, v4, v132
	v_add_f32_e32 v133, v5, v133
	v_mul_f32_e32 v169, 0xbfb8aa3b, v169
	v_mul_f32_e32 v160, 0xbfb8aa3b, v160
	v_mul_f32_e32 v154, 0xbfb8aa3b, v154
	v_mul_f32_e32 v155, 0xbfb8aa3b, v155
	v_mul_f32_e32 v156, 0xbfb8aa3b, v156
	v_mul_f32_e32 v157, 0xbfb8aa3b, v157
	v_mul_f32_e32 v150, 0xbfb8aa3b, v150
	v_mul_f32_e32 v151, 0xbfb8aa3b, v151
	v_mul_f32_e32 v152, 0xbfb8aa3b, v152
	v_mul_f32_e32 v153, 0xbfb8aa3b, v153
	v_mul_f32_e32 v146, 0xbfb8aa3b, v146
	v_mul_f32_e32 v147, 0xbfb8aa3b, v147
	v_mul_f32_e32 v148, 0xbfb8aa3b, v148
	v_mul_f32_e32 v149, 0xbfb8aa3b, v149
	v_mul_f32_e32 v142, 0xbfb8aa3b, v142
	v_mul_f32_e32 v143, 0xbfb8aa3b, v143
	v_mul_f32_e32 v144, 0xbfb8aa3b, v144
	v_mul_f32_e32 v145, 0xbfb8aa3b, v145
	v_mul_f32_e32 v138, 0xbfb8aa3b, v138
	v_mul_f32_e32 v139, 0xbfb8aa3b, v139
	v_mul_f32_e32 v140, 0xbfb8aa3b, v140
	v_mul_f32_e32 v141, 0xbfb8aa3b, v141
	v_mul_f32_e32 v134, 0xbfb8aa3b, v134
	v_mul_f32_e32 v135, 0xbfb8aa3b, v135
	v_mul_f32_e32 v136, 0xbfb8aa3b, v136
	v_mul_f32_e32 v137, 0xbfb8aa3b, v137
	v_mul_f32_e32 v130, 0xbfb8aa3b, v130
	v_mul_f32_e32 v131, 0xbfb8aa3b, v131
	v_mul_f32_e32 v132, 0xbfb8aa3b, v132
	v_mul_f32_e32 v133, 0xbfb8aa3b, v133
	v_exp_f32_e32 v169, v169
	v_exp_f32_e32 v160, v160
	v_exp_f32_e32 v154, v154
	v_exp_f32_e32 v155, v155
	v_exp_f32_e32 v156, v156
	v_exp_f32_e32 v157, v157
	v_exp_f32_e32 v150, v150
	v_exp_f32_e32 v151, v151
	v_exp_f32_e32 v152, v152
	v_exp_f32_e32 v153, v153
	v_exp_f32_e32 v146, v146
	v_exp_f32_e32 v147, v147
	v_exp_f32_e32 v148, v148
	v_exp_f32_e32 v149, v149
	v_exp_f32_e32 v142, v142
	v_exp_f32_e32 v143, v143
	v_exp_f32_e32 v144, v144
	v_exp_f32_e32 v145, v145
	v_exp_f32_e32 v138, v138
	v_exp_f32_e32 v139, v139
	v_exp_f32_e32 v140, v140
	v_exp_f32_e32 v141, v141
	v_exp_f32_e32 v134, v134
	v_exp_f32_e32 v135, v135
	v_exp_f32_e32 v136, v136
	v_exp_f32_e32 v137, v137
	v_exp_f32_e32 v130, v130
	v_exp_f32_e32 v131, v131
	v_exp_f32_e32 v132, v132
	v_exp_f32_e32 v133, v133
	v_add_f32_e32 v158, 1.0, v158
	v_add_f32_e32 v159, 1.0, v159
	v_rcp_f32_e32 v158, v158
	v_rcp_f32_e32 v159, v159
	v_add_f32_e32 v169, 1.0, v169
	v_add_f32_e32 v160, 1.0, v160
	v_add_f32_e32 v154, 1.0, v154
	v_add_f32_e32 v155, 1.0, v155
	v_add_f32_e32 v156, 1.0, v156
	v_add_f32_e32 v157, 1.0, v157
	v_add_f32_e32 v150, 1.0, v150
	v_add_f32_e32 v151, 1.0, v151
	v_add_f32_e32 v152, 1.0, v152
	v_add_f32_e32 v153, 1.0, v153
	v_add_f32_e32 v146, 1.0, v146
	v_add_f32_e32 v147, 1.0, v147
	v_add_f32_e32 v148, 1.0, v148
	v_add_f32_e32 v149, 1.0, v149
	v_add_f32_e32 v142, 1.0, v142
	v_add_f32_e32 v143, 1.0, v143
	v_add_f32_e32 v144, 1.0, v144
	v_add_f32_e32 v145, 1.0, v145
	v_add_f32_e32 v138, 1.0, v138
	v_add_f32_e32 v139, 1.0, v139
	v_add_f32_e32 v140, 1.0, v140
	v_add_f32_e32 v141, 1.0, v141
	v_add_f32_e32 v134, 1.0, v134
	v_add_f32_e32 v135, 1.0, v135
	v_add_f32_e32 v136, 1.0, v136
	v_add_f32_e32 v137, 1.0, v137
	v_add_f32_e32 v130, 1.0, v130
	v_add_f32_e32 v131, 1.0, v131
	v_add_f32_e32 v132, 1.0, v132
	v_add_f32_e32 v133, 1.0, v133
	v_rcp_f32_e32 v169, v169
	v_rcp_f32_e32 v161, v160
	v_rcp_f32_e32 v154, v154
	v_rcp_f32_e32 v155, v155
	v_rcp_f32_e32 v156, v156
	v_rcp_f32_e32 v157, v157
	v_rcp_f32_e32 v150, v150
	v_rcp_f32_e32 v151, v151
	v_rcp_f32_e32 v152, v152
	v_rcp_f32_e32 v153, v153
	v_rcp_f32_e32 v146, v146
	v_rcp_f32_e32 v147, v147
	v_rcp_f32_e32 v148, v148
	v_rcp_f32_e32 v149, v149
	v_rcp_f32_e32 v142, v142
	v_rcp_f32_e32 v143, v143
	v_rcp_f32_e32 v144, v144
	v_rcp_f32_e32 v145, v145
	v_rcp_f32_e32 v138, v138
	v_rcp_f32_e32 v139, v139
	v_rcp_f32_e32 v140, v140
	v_rcp_f32_e32 v141, v141
	v_rcp_f32_e32 v134, v134
	v_rcp_f32_e32 v135, v135
	v_rcp_f32_e32 v136, v136
	v_rcp_f32_e32 v137, v137
	v_rcp_f32_e32 v130, v130
	v_rcp_f32_e32 v131, v131
	v_rcp_f32_e32 v132, v132
	v_rcp_f32_e32 v133, v133
	s_mov_b64 s[0:1], 0x90000
	v_cvt_pk_bf16_f32 v232, v158, v159
	v_lshl_add_u64 v[158:159], v[170:171], 0, s[0:1]
	s_mov_b32 s0, 0x90000
	v_add_co_u32_e32 v170, vcc, s0, v170
	v_cvt_pk_bf16_f32 v231, v169, v175
	v_cvt_pk_bf16_f32 v233, v164, v161
	v_addc_co_u32_e32 v171, vcc, 0, v171, vcc
	v_cvt_pk_bf16_f32 v234, v154, v155
	v_cvt_pk_bf16_f32 v235, v156, v157
	v_cvt_pk_bf16_f32 v236, v150, v151
	v_cvt_pk_bf16_f32 v237, v152, v153
	v_cvt_pk_bf16_f32 v238, v146, v147
	v_cvt_pk_bf16_f32 v239, v148, v149
	v_cvt_pk_bf16_f32 v178, v142, v143
	v_cvt_pk_bf16_f32 v179, v144, v145
	v_cvt_pk_bf16_f32 v180, v138, v139
	v_cvt_pk_bf16_f32 v181, v140, v141
	v_cvt_pk_bf16_f32 v182, v134, v135
	v_cvt_pk_bf16_f32 v183, v136, v137
	v_cvt_pk_bf16_f32 v184, v130, v131
	v_cvt_pk_bf16_f32 v185, v132, v133
	s_nop 1
	v_permlane16_swap_b32_e32 v224, v226
	v_permlane16_swap_b32_e32 v225, v227
	v_permlane16_swap_b32_e32 v228, v230
	v_permlane16_swap_b32_e32 v229, v231
	v_lshl_add_u64 v[240:241], v[172:173], 0, v[244:245]
	global_store_dwordx4 v[240:241], v[224:227], off offset:256
	global_store_dwordx4 v[240:241], v[228:231], off offset:320
	s_nop 1
	v_permlane16_swap_b32_e32 v232, v234
	v_permlane16_swap_b32_e32 v233, v235
	v_permlane16_swap_b32_e32 v236, v238
	v_permlane16_swap_b32_e32 v237, v239
	v_lshl_add_u64 v[240:241], v[158:159], 0, v[244:245]
	global_store_dwordx4 v[240:241], v[232:235], off
	global_store_dwordx4 v[240:241], v[236:239], off offset:64
	s_nop 1
	v_permlane16_swap_b32_e32 v178, v180
	v_permlane16_swap_b32_e32 v179, v181
	v_permlane16_swap_b32_e32 v182, v184
	v_permlane16_swap_b32_e32 v183, v185
	v_lshl_add_u64 v[240:241], v[158:159], 0, v[244:245]
	global_store_dwordx4 v[240:241], v[178:181], off offset:256
	global_store_dwordx4 v[240:241], v[182:185], off offset:320
.LBB0_159:
	s_andn2_b64 vcc, exec, s[8:9]
	s_cbranch_vccnz .LBB0_161
	v_mbcnt_lo_u32_b32 v244, -1, 0
	v_mbcnt_hi_u32_b32 v244, -1, v244
	v_bfe_u32 v244, v244, 4, 1
	v_mul_u32_u24_e32 v244, 24, v244
	v_mov_b32_e32 v245, 0
	s_cmp_lt_u32 s94, 8
	s_cselect_b64 vcc, -1, 0
	s_and_b64 s[8:9], vcc, exec
	s_cselect_b32 s0, -4, -8
	v_and_b32_e32 v131, 64, v219
	s_add_i32 s0, s0, s94
	v_xor_b32_e32 v130, 16, v219
	v_add_u32_e32 v131, 64, v131
	s_and_b64 s[8:9], vcc, exec
	v_readlane_b32 s52, v249, 0
	v_cndmask_b32_e32 v152, 1.0, v218, vcc
	v_cmp_lt_i32_e32 vcc, v130, v131
	v_readlane_b32 s53, v249, 1
	v_readlane_b32 s54, v249, 2
	v_readlane_b32 s55, v249, 3
	v_cndmask_b32_e32 v130, v219, v130, vcc
	s_cselect_b32 s9, s53, s55
	s_cselect_b32 s8, s52, s54
	s_cselect_b32 s1, s71, s73
	s_cselect_b32 s11, s70, s72
	v_lshlrev_b32_e32 v154, 2, v130
	v_xor_b32_e32 v130, 32, v219
	s_lshl_b32 s0, s0, 9
	v_cmp_lt_i32_e32 vcc, v130, v131
	s_add_u32 s14, s11, s0
	s_addc_u32 s15, s1, 0
	v_cndmask_b32_e32 v130, v219, v130, vcc
	v_ashrrev_i32_e32 v167, 31, v166
	v_ashrrev_i32_e32 v169, 31, v168
	v_lshlrev_b32_e32 v153, 2, v130
	v_lshl_add_u64 v[130:131], v[166:167], 1, s[14:15]
	v_lshlrev_b64 v[132:133], 11, v[168:169]
	v_lshl_add_u64 v[146:147], v[130:131], 0, v[132:133]
	v_mov_b32_e32 v132, v127
	v_mov_b32_e32 v133, v123
	v_mov_b32_e32 v130, v126
	v_mov_b32_e32 v131, v122
	v_pk_mul_f32 v[132:133], v[132:133], v[132:133]
	v_mov_b32_e32 v158, v111
	v_pk_fma_f32 v[130:131], v[130:131], v[130:131], v[132:133]
	v_mov_b32_e32 v132, v128
	v_mov_b32_e32 v133, v124
	v_pk_fma_f32 v[130:131], v[132:133], v[132:133], v[130:131]
	v_mov_b32_e32 v132, v129
	v_mov_b32_e32 v133, v125
	v_pk_fma_f32 v[148:149], v[132:133], v[132:133], v[130:131]
	v_mov_b32_e32 v132, v119
	v_mov_b32_e32 v133, v115
	v_mov_b32_e32 v130, v118
	v_mov_b32_e32 v131, v114
	v_pk_mul_f32 v[132:133], v[132:133], v[132:133]
	v_mov_b32_e32 v159, v107
	v_pk_fma_f32 v[130:131], v[130:131], v[130:131], v[132:133]
	v_mov_b32_e32 v132, v120
	v_mov_b32_e32 v133, v116
	v_pk_fma_f32 v[130:131], v[132:133], v[132:133], v[130:131]
	v_mov_b32_e32 v132, v121
	v_mov_b32_e32 v133, v117
	v_pk_fma_f32 v[150:151], v[132:133], v[132:133], v[130:131]
	global_load_dwordx4 v[130:133], v216, s[8:9]
	global_load_dwordx4 v[134:137], v216, s[8:9] offset:64
	global_load_dwordx4 v[138:141], v216, s[8:9] offset:128
	global_load_dwordx4 v[142:145], v216, s[8:9] offset:192
	v_mov_b32_e32 v156, v110
	v_mov_b32_e32 v157, v106
	v_pk_mul_f32 v[158:159], v[158:159], v[158:159]
	v_mov_b32_e32 v160, v103
	v_pk_fma_f32 v[156:157], v[156:157], v[156:157], v[158:159]
	v_mov_b32_e32 v158, v112
	v_mov_b32_e32 v159, v108
	v_pk_fma_f32 v[156:157], v[158:159], v[158:159], v[156:157]
	v_mov_b32_e32 v158, v113
	v_mov_b32_e32 v159, v109
	v_mov_b32_e32 v161, v99
	v_pk_fma_f32 v[156:157], v[158:159], v[158:159], v[156:157]
	v_mov_b32_e32 v158, v102
	v_mov_b32_e32 v159, v98
	v_pk_mul_f32 v[160:161], v[160:161], v[160:161]
	s_mov_b32 s8, 0x358637bd
	v_pk_fma_f32 v[158:159], v[158:159], v[158:159], v[160:161]
	v_mov_b32_e32 v160, v104
	v_mov_b32_e32 v161, v100
	v_pk_fma_f32 v[158:159], v[160:161], v[160:161], v[158:159]
	v_mov_b32_e32 v160, v105
	v_mov_b32_e32 v161, v101
	v_pk_fma_f32 v[158:159], v[160:161], v[160:161], v[158:159]
	v_mov_b32_e32 v160, v156
	v_mov_b32_e32 v161, v148
	v_mov_b32_e32 v148, v157
	v_pk_add_f32 v[148:149], v[160:161], v[148:149]
	v_mov_b32_e32 v156, v158
	v_mov_b32_e32 v157, v150
	v_pk_add_f32 v[148:149], v[148:149], v[156:157]
	v_mov_b32_e32 v150, v159
	v_pk_add_f32 v[148:149], v[148:149], v[150:151]
	ds_bpermute_b32 v151, v154, v149
	ds_bpermute_b32 v150, v154, v148
	s_mov_b32 s4, 0x3c800000
	s_mov_b32 s1, 0x800000
	s_mov_b32 s0, 0x8000
	s_mov_b64 s[6:7], 0x8000
	s_waitcnt lgkmcnt(0)
	v_pk_add_f32 v[148:149], v[148:149], v[150:151]
	ds_bpermute_b32 v151, v153, v149
	ds_bpermute_b32 v150, v153, v148
	v_readlane_b32 s56, v249, 4
	v_readlane_b32 s57, v249, 5
	v_readlane_b32 s58, v249, 6
	v_readlane_b32 s59, v249, 7
	s_waitcnt lgkmcnt(0)
	v_pk_add_f32 v[150:151], v[148:149], v[150:151]
	v_mov_b64_e32 v[148:149], s[8:9]
	v_pk_fma_f32 v[150:151], v[150:151], s[4:5], v[148:149] op_sel_hi:[1,0,0]
	v_readlane_b32 s60, v249, 8
	v_mul_f32_e32 v155, 0x4b800000, v151
	v_cmp_gt_f32_e64 s[8:9], s1, v151
	v_cmp_gt_f32_e32 vcc, s1, v150
	v_readlane_b32 s61, v249, 9
	v_cndmask_b32_e64 v151, v151, v155, s[8:9]
	v_rsq_f32_e32 v151, v151
	v_readlane_b32 s62, v249, 10
	v_readlane_b32 s63, v249, 11
	v_readlane_b32 s64, v249, 12
	v_mul_f32_e32 v155, 0x45800000, v151
	v_cndmask_b32_e64 v151, v151, v155, s[8:9]
	v_mul_f32_e32 v156, v152, v151
	v_pk_mul_f32 v[158:159], v[126:127], v[156:157] op_sel_hi:[1,0]
	v_pk_mul_f32 v[160:161], v[128:129], v[156:157] op_sel_hi:[1,0]
	v_mul_f32_e32 v151, 0x4b800000, v150
	v_cndmask_b32_e32 v150, v150, v151, vcc
	v_pk_mul_f32 v[170:171], v[124:125], v[156:157] op_sel_hi:[1,0]
	v_rsq_f32_e32 v150, v150
	v_pk_mul_f32 v[172:173], v[120:121], v[156:157] op_sel_hi:[1,0]
	v_readlane_b32 s65, v249, 13
	v_readlane_b32 s66, v249, 14
	v_mul_f32_e32 v151, 0x45800000, v150
	v_cndmask_b32_e32 v150, v150, v151, vcc
	v_mul_f32_e32 v150, v152, v150
	v_readlane_b32 s67, v249, 15
	s_waitcnt vmcnt(3)
	v_pk_mul_f32 v[158:159], v[130:131], v[158:159]
	v_pk_mul_f32 v[160:161], v[132:133], v[160:161]
	v_cvt_pk_bf16_f32 v224, v158, v159
	v_cvt_pk_bf16_f32 v225, v160, v161
	v_pk_mul_f32 v[160:161], v[122:123], v[156:157] op_sel_hi:[1,0]
	s_waitcnt vmcnt(2)
	v_pk_mul_f32 v[170:171], v[136:137], v[170:171]
	v_pk_mul_f32 v[160:161], v[134:135], v[160:161]
	s_waitcnt vmcnt(1)
	v_pk_mul_f32 v[172:173], v[140:141], v[172:173]
	v_cvt_pk_bf16_f32 v226, v160, v161
	v_cvt_pk_bf16_f32 v227, v170, v171
	v_pk_mul_f32 v[170:171], v[118:119], v[156:157] op_sel_hi:[1,0]
	s_nop 0
	v_pk_mul_f32 v[170:171], v[138:139], v[170:171]
	s_nop 0
	v_cvt_pk_bf16_f32 v228, v170, v171
	v_cvt_pk_bf16_f32 v229, v172, v173
	v_pk_mul_f32 v[172:173], v[114:115], v[156:157] op_sel_hi:[1,0]
	v_pk_mul_f32 v[156:157], v[116:117], v[156:157] op_sel_hi:[1,0]
	s_waitcnt vmcnt(0)
	v_pk_mul_f32 v[172:173], v[142:143], v[172:173]
	v_pk_mul_f32 v[156:157], v[144:145], v[156:157]
	v_cvt_pk_bf16_f32 v230, v172, v173
	v_cvt_pk_bf16_f32 v231, v156, v157
	s_nop 1
	v_permlane16_swap_b32_e32 v224, v226
	v_permlane16_swap_b32_e32 v225, v227
	v_permlane16_swap_b32_e32 v228, v230
	v_permlane16_swap_b32_e32 v229, v231
	v_lshl_add_u64 v[240:241], v[146:147], 0, v[244:245]
	global_store_dwordx4 v[240:241], v[224:227], off
	global_store_dwordx4 v[240:241], v[228:231], off offset:64
	v_pk_mul_f32 v[156:157], v[110:111], v[150:151] op_sel_hi:[1,0]
	v_pk_mul_f32 v[158:159], v[112:113], v[150:151] op_sel_hi:[1,0]
	v_pk_mul_f32 v[156:157], v[130:131], v[156:157]
	v_pk_mul_f32 v[158:159], v[132:133], v[158:159]
	v_cvt_pk_bf16_f32 v232, v156, v157
	v_cvt_pk_bf16_f32 v233, v158, v159
	v_pk_mul_f32 v[156:157], v[106:107], v[150:151] op_sel_hi:[1,0]
	v_pk_mul_f32 v[158:159], v[108:109], v[150:151] op_sel_hi:[1,0]
	v_pk_mul_f32 v[156:157], v[134:135], v[156:157]
	v_pk_mul_f32 v[158:159], v[136:137], v[158:159]
	v_cvt_pk_bf16_f32 v234, v156, v157
	v_cvt_pk_bf16_f32 v235, v158, v159
	v_pk_mul_f32 v[156:157], v[102:103], v[150:151] op_sel_hi:[1,0]
	v_pk_mul_f32 v[158:159], v[104:105], v[150:151] op_sel_hi:[1,0]
	v_pk_mul_f32 v[156:157], v[138:139], v[156:157]
	v_pk_mul_f32 v[158:159], v[140:141], v[158:159]
	v_cvt_pk_bf16_f32 v236, v156, v157
	v_cvt_pk_bf16_f32 v237, v158, v159
	v_pk_mul_f32 v[156:157], v[98:99], v[150:151] op_sel_hi:[1,0]
	v_pk_mul_f32 v[150:151], v[100:101], v[150:151] op_sel_hi:[1,0]
	v_pk_mul_f32 v[156:157], v[142:143], v[156:157]
	v_pk_mul_f32 v[150:151], v[144:145], v[150:151]
	v_cvt_pk_bf16_f32 v238, v156, v157
	v_cvt_pk_bf16_f32 v239, v150, v151
	v_mov_b32_e32 v158, v95
	v_mov_b32_e32 v159, v91
	s_nop 1
	v_permlane16_swap_b32_e32 v232, v234
	v_permlane16_swap_b32_e32 v233, v235
	v_permlane16_swap_b32_e32 v236, v238
	v_permlane16_swap_b32_e32 v237, v239
	v_lshl_add_u64 v[240:241], v[146:147], 0, v[244:245]
	global_store_dwordx4 v[240:241], v[232:235], off offset:256
	global_store_dwordx4 v[240:241], v[236:239], off offset:320
	v_mov_b32_e32 v156, v94
	v_mov_b32_e32 v157, v90
	v_pk_mul_f32 v[158:159], v[158:159], v[158:159]
	v_mov_b32_e32 v160, v87
	v_pk_fma_f32 v[156:157], v[156:157], v[156:157], v[158:159]
	v_mov_b32_e32 v158, v96
	v_mov_b32_e32 v159, v92
	v_pk_fma_f32 v[156:157], v[158:159], v[158:159], v[156:157]
	v_mov_b32_e32 v158, v97
	v_mov_b32_e32 v159, v93
	v_mov_b32_e32 v161, v83
	v_pk_fma_f32 v[156:157], v[158:159], v[158:159], v[156:157]
	v_mov_b32_e32 v158, v86
	v_mov_b32_e32 v159, v82
	v_pk_mul_f32 v[160:161], v[160:161], v[160:161]
	v_mov_b32_e32 v170, v79
	v_pk_fma_f32 v[158:159], v[158:159], v[158:159], v[160:161]
	v_mov_b32_e32 v160, v88
	v_mov_b32_e32 v161, v84
	v_pk_fma_f32 v[158:159], v[160:161], v[160:161], v[158:159]
	v_mov_b32_e32 v160, v89
	v_mov_b32_e32 v161, v85
	v_mov_b32_e32 v171, v75
	v_pk_fma_f32 v[158:159], v[160:161], v[160:161], v[158:159]
	v_mov_b32_e32 v160, v78
	v_mov_b32_e32 v161, v74
	v_pk_mul_f32 v[170:171], v[170:171], v[170:171]
	v_mov_b32_e32 v172, v71
	v_pk_fma_f32 v[160:161], v[160:161], v[160:161], v[170:171]
	v_mov_b32_e32 v170, v80
	v_mov_b32_e32 v171, v76
	v_pk_fma_f32 v[160:161], v[170:171], v[170:171], v[160:161]
	v_mov_b32_e32 v170, v81
	v_mov_b32_e32 v171, v77
	v_mov_b32_e32 v173, v67
	v_pk_fma_f32 v[160:161], v[170:171], v[170:171], v[160:161]
	v_mov_b32_e32 v170, v70
	v_mov_b32_e32 v171, v66
	v_pk_mul_f32 v[172:173], v[172:173], v[172:173]
	v_lshl_add_u64 v[150:151], v[146:147], 0, s[6:7]
	v_pk_fma_f32 v[170:171], v[170:171], v[170:171], v[172:173]
	v_mov_b32_e32 v172, v72
	v_mov_b32_e32 v173, v68
	v_pk_fma_f32 v[170:171], v[172:173], v[172:173], v[170:171]
	v_mov_b32_e32 v172, v73
	v_mov_b32_e32 v173, v69
	v_pk_fma_f32 v[170:171], v[172:173], v[172:173], v[170:171]
	v_mov_b32_e32 v172, v160
	v_mov_b32_e32 v173, v156
	v_mov_b32_e32 v156, v161
	v_pk_add_f32 v[156:157], v[172:173], v[156:157]
	v_mov_b32_e32 v160, v170
	v_mov_b32_e32 v161, v158
	v_pk_add_f32 v[156:157], v[156:157], v[160:161]
	v_mov_b32_e32 v158, v171
	v_pk_add_f32 v[156:157], v[156:157], v[158:159]
	ds_bpermute_b32 v159, v154, v157
	ds_bpermute_b32 v158, v154, v156
	v_mov_b32_e32 v172, v39
	v_mov_b32_e32 v173, v35
	v_pk_mul_f32 v[172:173], v[172:173], v[172:173]
	s_waitcnt lgkmcnt(0)
	v_pk_add_f32 v[156:157], v[156:157], v[158:159]
	ds_bpermute_b32 v159, v153, v157
	ds_bpermute_b32 v158, v153, v156
	s_waitcnt lgkmcnt(0)
	v_pk_add_f32 v[156:157], v[156:157], v[158:159]
	s_nop 0
	v_pk_fma_f32 v[156:157], v[156:157], s[4:5], v[148:149] op_sel_hi:[1,0,0]
	s_nop 0
	v_mul_f32_e32 v155, 0x4b800000, v157
	v_cmp_gt_f32_e64 s[8:9], s1, v157
	v_cmp_gt_f32_e32 vcc, s1, v156
	s_nop 0
	v_cndmask_b32_e64 v155, v157, v155, s[8:9]
	v_rsq_f32_e32 v155, v155
	s_nop 0
	v_mul_f32_e32 v157, 0x45800000, v155
	v_cndmask_b32_e64 v155, v155, v157, s[8:9]
	v_mul_f32_e32 v158, v152, v155
	v_pk_mul_f32 v[160:161], v[94:95], v[158:159] op_sel_hi:[1,0]
	v_pk_mul_f32 v[170:171], v[96:97], v[158:159] op_sel_hi:[1,0]
	v_pk_mul_f32 v[160:161], v[130:131], v[160:161]
	v_pk_mul_f32 v[170:171], v[132:133], v[170:171]
	v_cvt_pk_bf16_f32 v178, v160, v161
	v_cvt_pk_bf16_f32 v179, v170, v171
	v_add_co_u32_e64 v170, s[8:9], s0, v146
	v_mul_f32_e32 v155, 0x4b800000, v156
	s_nop 0
	v_addc_co_u32_e64 v171, s[8:9], 0, v147, s[8:9]
	v_pk_mul_f32 v[160:161], v[90:91], v[158:159] op_sel_hi:[1,0]
	v_pk_mul_f32 v[170:171], v[92:93], v[158:159] op_sel_hi:[1,0]
	v_pk_mul_f32 v[160:161], v[134:135], v[160:161]
	v_pk_mul_f32 v[170:171], v[136:137], v[170:171]
	v_cndmask_b32_e32 v155, v156, v155, vcc
	v_cvt_pk_bf16_f32 v180, v160, v161
	v_cvt_pk_bf16_f32 v181, v170, v171
	v_rsq_f32_e32 v155, v155
	v_pk_mul_f32 v[160:161], v[86:87], v[158:159] op_sel_hi:[1,0]
	v_pk_mul_f32 v[170:171], v[88:89], v[158:159] op_sel_hi:[1,0]
	v_pk_mul_f32 v[160:161], v[138:139], v[160:161]
	v_pk_mul_f32 v[170:171], v[140:141], v[170:171]
	v_cvt_pk_bf16_f32 v182, v160, v161
	v_cvt_pk_bf16_f32 v183, v170, v171
	v_pk_mul_f32 v[160:161], v[82:83], v[158:159] op_sel_hi:[1,0]
	v_pk_mul_f32 v[158:159], v[84:85], v[158:159] op_sel_hi:[1,0]
	v_mul_f32_e32 v156, 0x45800000, v155
	v_pk_mul_f32 v[160:161], v[142:143], v[160:161]
	v_pk_mul_f32 v[158:159], v[144:145], v[158:159]
	v_cndmask_b32_e32 v155, v155, v156, vcc
	v_cvt_pk_bf16_f32 v184, v160, v161
	v_cvt_pk_bf16_f32 v185, v158, v159
	v_mul_f32_e32 v156, v152, v155
	s_nop 1
	v_permlane16_swap_b32_e32 v178, v180
	v_permlane16_swap_b32_e32 v179, v181
	v_permlane16_swap_b32_e32 v182, v184
	v_permlane16_swap_b32_e32 v183, v185
	v_lshl_add_u64 v[240:241], v[150:151], 0, v[244:245]
	global_store_dwordx4 v[240:241], v[178:181], off
	global_store_dwordx4 v[240:241], v[182:185], off offset:64
	v_pk_mul_f32 v[158:159], v[78:79], v[156:157] op_sel_hi:[1,0]
	v_pk_mul_f32 v[160:161], v[80:81], v[156:157] op_sel_hi:[1,0]
	v_pk_mul_f32 v[158:159], v[130:131], v[158:159]
	v_pk_mul_f32 v[160:161], v[132:133], v[160:161]
	v_cvt_pk_bf16_f32 v186, v158, v159
	v_cvt_pk_bf16_f32 v187, v160, v161
	v_pk_mul_f32 v[158:159], v[74:75], v[156:157] op_sel_hi:[1,0]
	v_pk_mul_f32 v[160:161], v[76:77], v[156:157] op_sel_hi:[1,0]
	v_pk_mul_f32 v[158:159], v[134:135], v[158:159]
	v_pk_mul_f32 v[160:161], v[136:137], v[160:161]
	v_cvt_pk_bf16_f32 v188, v158, v159
	v_cvt_pk_bf16_f32 v189, v160, v161
	v_pk_mul_f32 v[158:159], v[70:71], v[156:157] op_sel_hi:[1,0]
	v_pk_mul_f32 v[160:161], v[72:73], v[156:157] op_sel_hi:[1,0]
	v_pk_mul_f32 v[158:159], v[138:139], v[158:159]
	v_pk_mul_f32 v[160:161], v[140:141], v[160:161]
	v_cvt_pk_bf16_f32 v190, v158, v159
	v_cvt_pk_bf16_f32 v191, v160, v161
	v_pk_mul_f32 v[158:159], v[66:67], v[156:157] op_sel_hi:[1,0]
	v_pk_mul_f32 v[156:157], v[68:69], v[156:157] op_sel_hi:[1,0]
	v_pk_mul_f32 v[158:159], v[142:143], v[158:159]
	v_pk_mul_f32 v[156:157], v[144:145], v[156:157]
	v_cvt_pk_bf16_f32 v192, v158, v159
	v_cvt_pk_bf16_f32 v193, v156, v157
	s_nop 1
	v_permlane16_swap_b32_e32 v186, v188
	v_permlane16_swap_b32_e32 v187, v189
	v_permlane16_swap_b32_e32 v190, v192
	v_permlane16_swap_b32_e32 v191, v193
	v_lshl_add_u64 v[240:241], v[150:151], 0, v[244:245]
	global_store_dwordx4 v[240:241], v[186:189], off offset:256
	global_store_dwordx4 v[240:241], v[190:193], off offset:320
	v_mov_b32_e32 v158, v63
	v_mov_b32_e32 v159, v59
	v_mov_b32_e32 v156, v62
	v_mov_b32_e32 v157, v58
	v_pk_mul_f32 v[158:159], v[158:159], v[158:159]
	v_mov_b32_e32 v160, v55
	v_pk_fma_f32 v[156:157], v[156:157], v[156:157], v[158:159]
	v_mov_b32_e32 v158, v64
	v_mov_b32_e32 v159, v60
	v_pk_fma_f32 v[156:157], v[158:159], v[158:159], v[156:157]
	v_mov_b32_e32 v158, v65
	v_mov_b32_e32 v159, v61
	v_mov_b32_e32 v161, v51
	v_pk_fma_f32 v[156:157], v[158:159], v[158:159], v[156:157]
	v_mov_b32_e32 v158, v54
	v_mov_b32_e32 v159, v50
	v_pk_mul_f32 v[160:161], v[160:161], v[160:161]
	v_mov_b32_e32 v170, v47
	v_pk_fma_f32 v[158:159], v[158:159], v[158:159], v[160:161]
	v_mov_b32_e32 v160, v56
	v_mov_b32_e32 v161, v52
	v_pk_fma_f32 v[158:159], v[160:161], v[160:161], v[158:159]
	v_mov_b32_e32 v160, v57
	v_mov_b32_e32 v161, v53
	v_mov_b32_e32 v171, v43
	v_pk_fma_f32 v[158:159], v[160:161], v[160:161], v[158:159]
	v_mov_b32_e32 v160, v46
	v_mov_b32_e32 v161, v42
	v_pk_mul_f32 v[170:171], v[170:171], v[170:171]
	s_mov_b64 s[8:9], 0x40000
	v_pk_fma_f32 v[160:161], v[160:161], v[160:161], v[170:171]
	v_mov_b32_e32 v170, v48
	v_mov_b32_e32 v171, v44
	v_pk_fma_f32 v[160:161], v[170:171], v[170:171], v[160:161]
	v_mov_b32_e32 v170, v49
	v_mov_b32_e32 v171, v45
	v_pk_fma_f32 v[160:161], v[170:171], v[170:171], v[160:161]
	v_mov_b32_e32 v170, v38
	v_mov_b32_e32 v171, v34
	v_pk_fma_f32 v[170:171], v[170:171], v[170:171], v[172:173]
	v_mov_b32_e32 v172, v40
	v_mov_b32_e32 v173, v36
	v_pk_fma_f32 v[170:171], v[172:173], v[172:173], v[170:171]
	v_mov_b32_e32 v172, v41
	v_mov_b32_e32 v173, v37
	v_pk_fma_f32 v[170:171], v[172:173], v[172:173], v[170:171]
	v_mov_b32_e32 v172, v160
	v_mov_b32_e32 v173, v156
	v_mov_b32_e32 v156, v161
	v_pk_add_f32 v[156:157], v[172:173], v[156:157]
	v_mov_b32_e32 v160, v170
	v_mov_b32_e32 v161, v158
	v_pk_add_f32 v[156:157], v[156:157], v[160:161]
	v_mov_b32_e32 v158, v171
	v_pk_add_f32 v[156:157], v[156:157], v[158:159]
	ds_bpermute_b32 v159, v154, v157
	ds_bpermute_b32 v158, v154, v156
	v_lshl_add_u64 v[150:151], v[146:147], 0, s[8:9]
	s_mov_b32 s0, 0x40000
	v_mov_b32_e32 v172, v7
	v_mov_b32_e32 v173, v3
	s_waitcnt lgkmcnt(0)
	v_pk_add_f32 v[156:157], v[156:157], v[158:159]
	ds_bpermute_b32 v159, v153, v157
	ds_bpermute_b32 v158, v153, v156
	v_pk_mul_f32 v[172:173], v[172:173], v[172:173]
	s_waitcnt lgkmcnt(0)
	v_pk_add_f32 v[156:157], v[156:157], v[158:159]
	s_nop 0
	v_pk_fma_f32 v[156:157], v[156:157], s[4:5], v[148:149] op_sel_hi:[1,0,0]
	s_nop 0
	v_mul_f32_e32 v155, 0x4b800000, v157
	v_cmp_gt_f32_e64 s[8:9], s1, v157
	v_cmp_gt_f32_e32 vcc, s1, v156
	s_nop 0
	v_cndmask_b32_e64 v155, v157, v155, s[8:9]
	v_rsq_f32_e32 v155, v155
	s_nop 0
	v_mul_f32_e32 v157, 0x45800000, v155
	v_cndmask_b32_e64 v155, v155, v157, s[8:9]
	v_mul_f32_e32 v158, v152, v155
	v_pk_mul_f32 v[160:161], v[62:63], v[158:159] op_sel_hi:[1,0]
	v_pk_mul_f32 v[170:171], v[64:65], v[158:159] op_sel_hi:[1,0]
	v_pk_mul_f32 v[160:161], v[130:131], v[160:161]
	v_pk_mul_f32 v[170:171], v[132:133], v[170:171]
	v_cvt_pk_bf16_f32 v194, v160, v161
	v_cvt_pk_bf16_f32 v195, v170, v171
	v_add_co_u32_e64 v170, s[8:9], s0, v146
	v_mul_f32_e32 v155, 0x4b800000, v156
	s_nop 0
	v_addc_co_u32_e64 v171, s[8:9], 0, v147, s[8:9]
	v_pk_mul_f32 v[160:161], v[58:59], v[158:159] op_sel_hi:[1,0]
	v_pk_mul_f32 v[170:171], v[60:61], v[158:159] op_sel_hi:[1,0]
	v_pk_mul_f32 v[160:161], v[134:135], v[160:161]
	v_pk_mul_f32 v[170:171], v[136:137], v[170:171]
	v_cndmask_b32_e32 v155, v156, v155, vcc
	v_cvt_pk_bf16_f32 v196, v160, v161
	v_cvt_pk_bf16_f32 v197, v170, v171
	v_rsq_f32_e32 v155, v155
	v_pk_mul_f32 v[160:161], v[54:55], v[158:159] op_sel_hi:[1,0]
	v_pk_mul_f32 v[170:171], v[56:57], v[158:159] op_sel_hi:[1,0]
	v_pk_mul_f32 v[160:161], v[138:139], v[160:161]
	v_pk_mul_f32 v[170:171], v[140:141], v[170:171]
	v_cvt_pk_bf16_f32 v198, v160, v161
	v_cvt_pk_bf16_f32 v199, v170, v171
	v_pk_mul_f32 v[160:161], v[50:51], v[158:159] op_sel_hi:[1,0]
	v_pk_mul_f32 v[158:159], v[52:53], v[158:159] op_sel_hi:[1,0]
	v_mul_f32_e32 v156, 0x45800000, v155
	v_pk_mul_f32 v[160:161], v[142:143], v[160:161]
	v_pk_mul_f32 v[158:159], v[144:145], v[158:159]
	v_cndmask_b32_e32 v155, v155, v156, vcc
	v_cvt_pk_bf16_f32 v200, v160, v161
	v_cvt_pk_bf16_f32 v201, v158, v159
	v_mul_f32_e32 v156, v152, v155
	s_nop 1
	v_permlane16_swap_b32_e32 v194, v196
	v_permlane16_swap_b32_e32 v195, v197
	v_permlane16_swap_b32_e32 v198, v200
	v_permlane16_swap_b32_e32 v199, v201
	v_lshl_add_u64 v[240:241], v[150:151], 0, v[244:245]
	global_store_dwordx4 v[240:241], v[194:197], off
	global_store_dwordx4 v[240:241], v[198:201], off offset:64
	v_pk_mul_f32 v[158:159], v[46:47], v[156:157] op_sel_hi:[1,0]
	v_pk_mul_f32 v[160:161], v[48:49], v[156:157] op_sel_hi:[1,0]
	v_pk_mul_f32 v[158:159], v[130:131], v[158:159]
	v_pk_mul_f32 v[160:161], v[132:133], v[160:161]
	v_cvt_pk_bf16_f32 v224, v158, v159
	v_cvt_pk_bf16_f32 v225, v160, v161
	v_pk_mul_f32 v[158:159], v[42:43], v[156:157] op_sel_hi:[1,0]
	v_pk_mul_f32 v[160:161], v[44:45], v[156:157] op_sel_hi:[1,0]
	v_pk_mul_f32 v[158:159], v[134:135], v[158:159]
	v_pk_mul_f32 v[160:161], v[136:137], v[160:161]
	v_cvt_pk_bf16_f32 v226, v158, v159
	v_cvt_pk_bf16_f32 v227, v160, v161
	v_pk_mul_f32 v[158:159], v[38:39], v[156:157] op_sel_hi:[1,0]
	v_pk_mul_f32 v[160:161], v[40:41], v[156:157] op_sel_hi:[1,0]
	v_pk_mul_f32 v[158:159], v[138:139], v[158:159]
	v_pk_mul_f32 v[160:161], v[140:141], v[160:161]
	v_cvt_pk_bf16_f32 v228, v158, v159
	v_cvt_pk_bf16_f32 v229, v160, v161
	v_pk_mul_f32 v[158:159], v[34:35], v[156:157] op_sel_hi:[1,0]
	v_pk_mul_f32 v[156:157], v[36:37], v[156:157] op_sel_hi:[1,0]
	v_pk_mul_f32 v[158:159], v[142:143], v[158:159]
	v_pk_mul_f32 v[156:157], v[144:145], v[156:157]
	v_cvt_pk_bf16_f32 v230, v158, v159
	v_cvt_pk_bf16_f32 v231, v156, v157
	s_nop 1
	v_permlane16_swap_b32_e32 v224, v226
	v_permlane16_swap_b32_e32 v225, v227
	v_permlane16_swap_b32_e32 v228, v230
	v_permlane16_swap_b32_e32 v229, v231
	v_lshl_add_u64 v[240:241], v[150:151], 0, v[244:245]
	global_store_dwordx4 v[240:241], v[224:227], off offset:256
	global_store_dwordx4 v[240:241], v[228:231], off offset:320
	v_mov_b32_e32 v158, v31
	v_mov_b32_e32 v159, v27
	v_mov_b32_e32 v156, v30
	v_mov_b32_e32 v157, v26
	v_pk_mul_f32 v[158:159], v[158:159], v[158:159]
	v_mov_b32_e32 v160, v23
	v_pk_fma_f32 v[156:157], v[156:157], v[156:157], v[158:159]
	v_mov_b32_e32 v158, v32
	v_mov_b32_e32 v159, v28
	v_pk_fma_f32 v[156:157], v[158:159], v[158:159], v[156:157]
	v_mov_b32_e32 v158, v33
	v_mov_b32_e32 v159, v29
	v_mov_b32_e32 v161, v19
	v_pk_fma_f32 v[156:157], v[158:159], v[158:159], v[156:157]
	v_mov_b32_e32 v158, v22
	v_mov_b32_e32 v159, v18
	v_pk_mul_f32 v[160:161], v[160:161], v[160:161]
	v_mov_b32_e32 v170, v15
	v_pk_fma_f32 v[158:159], v[158:159], v[158:159], v[160:161]
	v_mov_b32_e32 v160, v24
	v_mov_b32_e32 v161, v20
	v_pk_fma_f32 v[158:159], v[160:161], v[160:161], v[158:159]
	v_mov_b32_e32 v160, v25
	v_mov_b32_e32 v161, v21
	v_mov_b32_e32 v171, v11
	v_pk_fma_f32 v[158:159], v[160:161], v[160:161], v[158:159]
	v_mov_b32_e32 v160, v14
	v_mov_b32_e32 v161, v10
	v_pk_mul_f32 v[170:171], v[170:171], v[170:171]
	s_mov_b64 s[8:9], 0x48000
	v_pk_fma_f32 v[160:161], v[160:161], v[160:161], v[170:171]
	v_mov_b32_e32 v170, v16
	v_mov_b32_e32 v171, v12
	v_pk_fma_f32 v[160:161], v[170:171], v[170:171], v[160:161]
	v_mov_b32_e32 v170, v17
	v_mov_b32_e32 v171, v13
	v_pk_fma_f32 v[160:161], v[170:171], v[170:171], v[160:161]
	v_mov_b32_e32 v170, v6
	v_mov_b32_e32 v171, v2
	v_pk_fma_f32 v[170:171], v[170:171], v[170:171], v[172:173]
	v_mov_b32_e32 v172, v8
	v_mov_b32_e32 v173, v4
	v_pk_fma_f32 v[170:171], v[172:173], v[172:173], v[170:171]
	v_mov_b32_e32 v172, v9
	v_mov_b32_e32 v173, v5
	v_pk_fma_f32 v[170:171], v[172:173], v[172:173], v[170:171]
	v_mov_b32_e32 v172, v160
	v_mov_b32_e32 v173, v156
	v_mov_b32_e32 v156, v161
	v_pk_add_f32 v[156:157], v[172:173], v[156:157]
	v_mov_b32_e32 v160, v170
	v_mov_b32_e32 v161, v158
	v_pk_add_f32 v[156:157], v[156:157], v[160:161]
	v_mov_b32_e32 v158, v171
	v_pk_add_f32 v[156:157], v[156:157], v[158:159]
	ds_bpermute_b32 v155, v154, v157
	ds_bpermute_b32 v154, v154, v156
	v_lshl_add_u64 v[150:151], v[146:147], 0, s[8:9]
	s_mov_b32 s0, 0x48000
	s_waitcnt lgkmcnt(0)
	v_pk_add_f32 v[154:155], v[156:157], v[154:155]
	ds_bpermute_b32 v157, v153, v155
	ds_bpermute_b32 v156, v153, v154
	s_waitcnt lgkmcnt(0)
	v_pk_add_f32 v[154:155], v[154:155], v[156:157]
	s_nop 0
	v_pk_fma_f32 v[148:149], v[154:155], s[4:5], v[148:149] op_sel_hi:[1,0,0]
	s_nop 0
	v_mul_f32_e32 v153, 0x4b800000, v149
	v_cmp_gt_f32_e64 s[8:9], s1, v149
	v_cmp_gt_f32_e32 vcc, s1, v148
	s_nop 0
	v_cndmask_b32_e64 v149, v149, v153, s[8:9]
	v_rsq_f32_e32 v149, v149
	s_nop 0
	v_mul_f32_e32 v153, 0x45800000, v149
	v_cndmask_b32_e64 v149, v149, v153, s[8:9]
	v_mul_f32_e32 v154, v152, v149
	v_pk_mul_f32 v[156:157], v[30:31], v[154:155] op_sel_hi:[1,0]
	v_pk_mul_f32 v[158:159], v[32:33], v[154:155] op_sel_hi:[1,0]
	v_pk_mul_f32 v[156:157], v[130:131], v[156:157]
	v_pk_mul_f32 v[158:159], v[132:133], v[158:159]
	v_add_co_u32_e64 v146, s[8:9], s0, v146
	v_cvt_pk_bf16_f32 v232, v156, v157
	v_cvt_pk_bf16_f32 v233, v158, v159
	v_addc_co_u32_e64 v147, s[8:9], 0, v147, s[8:9]
	v_pk_mul_f32 v[146:147], v[26:27], v[154:155] op_sel_hi:[1,0]
	v_pk_mul_f32 v[156:157], v[28:29], v[154:155] op_sel_hi:[1,0]
	v_pk_mul_f32 v[146:147], v[134:135], v[146:147]
	v_pk_mul_f32 v[156:157], v[136:137], v[156:157]
	v_cvt_pk_bf16_f32 v234, v146, v147
	v_cvt_pk_bf16_f32 v235, v156, v157
	v_pk_mul_f32 v[146:147], v[22:23], v[154:155] op_sel_hi:[1,0]
	v_pk_mul_f32 v[156:157], v[24:25], v[154:155] op_sel_hi:[1,0]
	v_pk_mul_f32 v[146:147], v[138:139], v[146:147]
	v_pk_mul_f32 v[156:157], v[140:141], v[156:157]
	v_cvt_pk_bf16_f32 v236, v146, v147
	v_cvt_pk_bf16_f32 v237, v156, v157
	v_pk_mul_f32 v[146:147], v[18:19], v[154:155] op_sel_hi:[1,0]
	v_pk_mul_f32 v[154:155], v[20:21], v[154:155] op_sel_hi:[1,0]
	v_pk_mul_f32 v[146:147], v[142:143], v[146:147]
	v_pk_mul_f32 v[154:155], v[144:145], v[154:155]
	v_cvt_pk_bf16_f32 v238, v146, v147
	v_cvt_pk_bf16_f32 v239, v154, v155
	s_nop 1
	v_permlane16_swap_b32_e32 v232, v234
	v_permlane16_swap_b32_e32 v233, v235
	v_permlane16_swap_b32_e32 v236, v238
	v_permlane16_swap_b32_e32 v237, v239
	v_lshl_add_u64 v[240:241], v[150:151], 0, v[244:245]
	global_store_dwordx4 v[240:241], v[232:235], off
	global_store_dwordx4 v[240:241], v[236:239], off offset:64
	v_mul_f32_e32 v146, 0x4b800000, v148
	v_cndmask_b32_e32 v146, v148, v146, vcc
	v_rsq_f32_e32 v146, v146
	s_nop 0
	v_mul_f32_e32 v147, 0x45800000, v146
	v_cndmask_b32_e32 v146, v146, v147, vcc
	v_mul_f32_e32 v146, v152, v146
	v_pk_mul_f32 v[148:149], v[14:15], v[146:147] op_sel_hi:[1,0]
	s_nop 0
	v_pk_mul_f32 v[130:131], v[130:131], v[148:149]
	v_pk_mul_f32 v[148:149], v[16:17], v[146:147] op_sel_hi:[1,0]
	v_cvt_pk_bf16_f32 v178, v130, v131
	v_pk_mul_f32 v[132:133], v[132:133], v[148:149]
	s_nop 0
	v_cvt_pk_bf16_f32 v179, v132, v133
	v_pk_mul_f32 v[130:131], v[10:11], v[146:147] op_sel_hi:[1,0]
	v_pk_mul_f32 v[132:133], v[12:13], v[146:147] op_sel_hi:[1,0]
	v_pk_mul_f32 v[130:131], v[134:135], v[130:131]
	v_pk_mul_f32 v[132:133], v[136:137], v[132:133]
	v_cvt_pk_bf16_f32 v180, v130, v131
	v_cvt_pk_bf16_f32 v181, v132, v133
	v_pk_mul_f32 v[130:131], v[6:7], v[146:147] op_sel_hi:[1,0]
	v_pk_mul_f32 v[132:133], v[8:9], v[146:147] op_sel_hi:[1,0]
	v_pk_mul_f32 v[130:131], v[138:139], v[130:131]
	v_pk_mul_f32 v[132:133], v[140:141], v[132:133]
	v_cvt_pk_bf16_f32 v182, v130, v131
	v_cvt_pk_bf16_f32 v183, v132, v133
	v_pk_mul_f32 v[130:131], v[2:3], v[146:147] op_sel_hi:[1,0]
	v_pk_mul_f32 v[132:133], v[4:5], v[146:147] op_sel_hi:[1,0]
	v_pk_mul_f32 v[130:131], v[142:143], v[130:131]
	v_pk_mul_f32 v[132:133], v[144:145], v[132:133]
	v_cvt_pk_bf16_f32 v184, v130, v131
	v_cvt_pk_bf16_f32 v185, v132, v133
	s_nop 1
	v_permlane16_swap_b32_e32 v178, v180
	v_permlane16_swap_b32_e32 v179, v181
	v_permlane16_swap_b32_e32 v182, v184
	v_permlane16_swap_b32_e32 v183, v185
	v_lshl_add_u64 v[240:241], v[150:151], 0, v[244:245]
	global_store_dwordx4 v[240:241], v[178:181], off offset:256
	global_store_dwordx4 v[240:241], v[182:185], off offset:320

.LBB0_181:
	s_andn2_b64 vcc, exec, s[8:9]
	s_cbranch_vccnz .LBB0_183
	v_mbcnt_lo_u32_b32 v244, -1, 0
	v_mbcnt_hi_u32_b32 v244, -1, v244
	v_bfe_u32 v244, v244, 4, 1
	v_mul_u32_u24_e32 v244, 24, v244
	v_mov_b32_e32 v245, 0
	v_mul_f32_e32 v132, 0x3d372713, v126
	v_mul_f32_e32 v133, 0x3d372713, v127
	v_mul_f32_e32 v132, v126, v132
	v_mul_f32_e32 v133, v127, v133
	v_fma_f32 v132, v126, v132, v126
	v_fma_f32 v133, v127, v133, v127
	v_mul_f32_e32 v132, 0xbfcc422a, v132
	v_mul_f32_e32 v133, 0xbfcc422a, v133
	v_mul_f32_e32 v132, 0x3fb8aa3b, v132
	v_mul_f32_e32 v133, 0x3fb8aa3b, v133
	v_exp_f32_e32 v132, v132
	v_exp_f32_e32 v133, v133
	v_ashrrev_i32_e32 v169, 31, v168
	s_lshl_b32 s8, s94, 8
	v_add_f32_e32 v132, 1.0, v132
	v_add_f32_e32 v133, 1.0, v133
	v_rcp_f32_e32 v132, v132
	v_rcp_f32_e32 v133, v133
	v_lshlrev_b64 v[130:131], 10, v[168:169]
	s_ashr_i32 s9, s8, 31
	v_ashrrev_i32_e32 v167, 31, v166
	v_pk_mul_f32 v[126:127], v[126:127], v[132:133]
	v_mul_f32_e32 v132, 0x3d372713, v128
	v_mul_f32_e32 v133, 0x3d372713, v129
	v_mul_f32_e32 v132, v128, v132
	v_mul_f32_e32 v133, v129, v133
	v_fma_f32 v132, v128, v132, v128
	v_fma_f32 v133, v129, v133, v129
	v_mul_f32_e32 v132, 0xbfcc422a, v132
	v_mul_f32_e32 v133, 0xbfcc422a, v133
	v_mul_f32_e32 v132, 0x3fb8aa3b, v132
	v_mul_f32_e32 v133, 0x3fb8aa3b, v133
	v_exp_f32_e32 v132, v132
	v_exp_f32_e32 v133, v133
	s_movk_i32 s0, 0x4000
	v_add_f32_e32 v132, 1.0, v132
	v_add_f32_e32 v133, 1.0, v133
	v_rcp_f32_e32 v132, v132
	v_rcp_f32_e32 v133, v133
	s_nop 0
	v_pk_mul_f32 v[128:129], v[128:129], v[132:133]
	s_nop 0
	v_cvt_pk_bf16_f32 v225, v128, v129
	v_mul_f32_e32 v128, 0x3d372713, v122
	v_mul_f32_e32 v129, 0x3d372713, v123
	v_mul_f32_e32 v128, v122, v128
	v_mul_f32_e32 v129, v123, v129
	v_fma_f32 v128, v122, v128, v122
	v_fma_f32 v129, v123, v129, v123
	v_mul_f32_e32 v128, 0xbfcc422a, v128
	v_mul_f32_e32 v129, 0xbfcc422a, v129
	v_mul_f32_e32 v128, 0x3fb8aa3b, v128
	v_mul_f32_e32 v129, 0x3fb8aa3b, v129
	v_exp_f32_e32 v128, v128
	v_exp_f32_e32 v129, v129
	v_cvt_pk_bf16_f32 v224, v126, v127
	v_lshl_add_u64 v[126:127], s[50:51], 0, v[130:131]
	v_add_f32_e32 v128, 1.0, v128
	v_add_f32_e32 v129, 1.0, v129
	v_rcp_f32_e32 v128, v128
	v_rcp_f32_e32 v129, v129
	v_lshl_add_u64 v[126:127], s[8:9], 1, v[126:127]
	v_lshl_add_u64 v[126:127], v[166:167], 1, v[126:127]
	s_mov_b64 s[8:9], 0x4000
	v_pk_mul_f32 v[122:123], v[122:123], v[128:129]
	v_mul_f32_e32 v128, 0x3d372713, v124
	v_mul_f32_e32 v129, 0x3d372713, v125
	v_mul_f32_e32 v128, v124, v128
	v_mul_f32_e32 v129, v125, v129
	v_fma_f32 v128, v124, v128, v124
	v_fma_f32 v129, v125, v129, v125
	v_mul_f32_e32 v128, 0xbfcc422a, v128
	v_mul_f32_e32 v129, 0xbfcc422a, v129
	v_mul_f32_e32 v128, 0x3fb8aa3b, v128
	v_mul_f32_e32 v129, 0x3fb8aa3b, v129
	v_exp_f32_e32 v128, v128
	v_exp_f32_e32 v129, v129
	v_cvt_pk_bf16_f32 v226, v122, v123
	v_add_f32_e32 v128, 1.0, v128
	v_add_f32_e32 v129, 1.0, v129
	v_rcp_f32_e32 v128, v128
	v_rcp_f32_e32 v129, v129
	s_nop 0
	v_pk_mul_f32 v[124:125], v[124:125], v[128:129]
	s_nop 0
	v_cvt_pk_bf16_f32 v227, v124, v125
	v_mul_f32_e32 v122, 0x3d372713, v118
	v_mul_f32_e32 v123, 0x3d372713, v119
	v_mul_f32_e32 v122, v118, v122
	v_mul_f32_e32 v123, v119, v123
	v_fma_f32 v122, v118, v122, v118
	v_fma_f32 v123, v119, v123, v119
	v_mul_f32_e32 v122, 0xbfcc422a, v122
	v_mul_f32_e32 v123, 0xbfcc422a, v123
	v_mul_f32_e32 v122, 0x3fb8aa3b, v122
	v_mul_f32_e32 v123, 0x3fb8aa3b, v123
	v_exp_f32_e32 v122, v122
	v_exp_f32_e32 v123, v123
	v_add_f32_e32 v122, 1.0, v122
	v_add_f32_e32 v123, 1.0, v123
	v_rcp_f32_e32 v122, v122
	v_rcp_f32_e32 v123, v123
	s_nop 0
	v_pk_mul_f32 v[118:119], v[118:119], v[122:123]
	v_mul_f32_e32 v122, 0x3d372713, v120
	v_mul_f32_e32 v123, 0x3d372713, v121
	v_mul_f32_e32 v122, v120, v122
	v_mul_f32_e32 v123, v121, v123
	v_fma_f32 v122, v120, v122, v120
	v_fma_f32 v123, v121, v123, v121
	v_mul_f32_e32 v122, 0xbfcc422a, v122
	v_mul_f32_e32 v123, 0xbfcc422a, v123
	v_mul_f32_e32 v122, 0x3fb8aa3b, v122
	v_mul_f32_e32 v123, 0x3fb8aa3b, v123
	v_exp_f32_e32 v122, v122
	v_exp_f32_e32 v123, v123
	v_cvt_pk_bf16_f32 v228, v118, v119
	v_add_f32_e32 v122, 1.0, v122
	v_add_f32_e32 v123, 1.0, v123
	v_rcp_f32_e32 v122, v122
	v_rcp_f32_e32 v123, v123
	s_nop 0
	v_pk_mul_f32 v[120:121], v[120:121], v[122:123]
	s_nop 0
	v_cvt_pk_bf16_f32 v229, v120, v121
	v_mul_f32_e32 v118, 0x3d372713, v114
	v_mul_f32_e32 v119, 0x3d372713, v115
	v_mul_f32_e32 v118, v114, v118
	v_mul_f32_e32 v119, v115, v119
	v_fma_f32 v118, v114, v118, v114
	v_fma_f32 v119, v115, v119, v115
	v_mul_f32_e32 v118, 0xbfcc422a, v118
	v_mul_f32_e32 v119, 0xbfcc422a, v119
	v_mul_f32_e32 v118, 0x3fb8aa3b, v118
	v_mul_f32_e32 v119, 0x3fb8aa3b, v119
	v_exp_f32_e32 v118, v118
	v_exp_f32_e32 v119, v119
	v_add_f32_e32 v118, 1.0, v118
	v_add_f32_e32 v119, 1.0, v119
	v_rcp_f32_e32 v118, v118
	v_rcp_f32_e32 v119, v119
	s_nop 0
	v_pk_mul_f32 v[114:115], v[114:115], v[118:119]
	v_mul_f32_e32 v118, 0x3d372713, v116
	v_mul_f32_e32 v119, 0x3d372713, v117
	v_mul_f32_e32 v118, v116, v118
	v_mul_f32_e32 v119, v117, v119
	v_fma_f32 v118, v116, v118, v116
	v_fma_f32 v119, v117, v119, v117
	v_mul_f32_e32 v118, 0xbfcc422a, v118
	v_mul_f32_e32 v119, 0xbfcc422a, v119
	v_mul_f32_e32 v118, 0x3fb8aa3b, v118
	v_mul_f32_e32 v119, 0x3fb8aa3b, v119
	v_exp_f32_e32 v118, v118
	v_exp_f32_e32 v119, v119
	v_cvt_pk_bf16_f32 v230, v114, v115
	v_add_f32_e32 v118, 1.0, v118
	v_add_f32_e32 v119, 1.0, v119
	v_rcp_f32_e32 v118, v118
	v_rcp_f32_e32 v119, v119
	s_nop 0
	v_pk_mul_f32 v[116:117], v[116:117], v[118:119]
	s_nop 0
	v_cvt_pk_bf16_f32 v231, v116, v117
	s_nop 1
	v_permlane16_swap_b32_e32 v224, v226
	v_permlane16_swap_b32_e32 v225, v227
	v_permlane16_swap_b32_e32 v228, v230
	v_permlane16_swap_b32_e32 v229, v231
	v_lshl_add_u64 v[240:241], v[126:127], 0, v[244:245]
	global_store_dwordx4 v[240:241], v[224:227], off
	global_store_dwordx4 v[240:241], v[228:231], off offset:64
	v_mul_f32_e32 v114, 0x3d372713, v110
	v_mul_f32_e32 v115, 0x3d372713, v111
	v_mul_f32_e32 v114, v110, v114
	v_mul_f32_e32 v115, v111, v115
	v_fma_f32 v114, v110, v114, v110
	v_fma_f32 v115, v111, v115, v111
	v_mul_f32_e32 v114, 0xbfcc422a, v114
	v_mul_f32_e32 v115, 0xbfcc422a, v115
	v_mul_f32_e32 v114, 0x3fb8aa3b, v114
	v_mul_f32_e32 v115, 0x3fb8aa3b, v115
	v_exp_f32_e32 v114, v114
	v_exp_f32_e32 v115, v115
	v_add_f32_e32 v114, 1.0, v114
	v_add_f32_e32 v115, 1.0, v115
	v_rcp_f32_e32 v114, v114
	v_rcp_f32_e32 v115, v115
	s_nop 0
	v_pk_mul_f32 v[110:111], v[110:111], v[114:115]
	v_mul_f32_e32 v114, 0x3d372713, v112
	v_mul_f32_e32 v115, 0x3d372713, v113
	v_mul_f32_e32 v114, v112, v114
	v_mul_f32_e32 v115, v113, v115
	v_fma_f32 v114, v112, v114, v112
	v_fma_f32 v115, v113, v115, v113
	v_mul_f32_e32 v114, 0xbfcc422a, v114
	v_mul_f32_e32 v115, 0xbfcc422a, v115
	v_mul_f32_e32 v114, 0x3fb8aa3b, v114
	v_mul_f32_e32 v115, 0x3fb8aa3b, v115
	v_exp_f32_e32 v114, v114
	v_exp_f32_e32 v115, v115
	v_cvt_pk_bf16_f32 v232, v110, v111
	v_add_f32_e32 v114, 1.0, v114
	v_add_f32_e32 v115, 1.0, v115
	v_rcp_f32_e32 v114, v114
	v_rcp_f32_e32 v115, v115
	s_nop 0
	v_pk_mul_f32 v[112:113], v[112:113], v[114:115]
	s_nop 0
	v_cvt_pk_bf16_f32 v233, v112, v113
	v_mul_f32_e32 v110, 0x3d372713, v106
	v_mul_f32_e32 v111, 0x3d372713, v107
	v_mul_f32_e32 v110, v106, v110
	v_mul_f32_e32 v111, v107, v111
	v_fma_f32 v110, v106, v110, v106
	v_fma_f32 v111, v107, v111, v107
	v_mul_f32_e32 v110, 0xbfcc422a, v110
	v_mul_f32_e32 v111, 0xbfcc422a, v111
	v_mul_f32_e32 v110, 0x3fb8aa3b, v110
	v_mul_f32_e32 v111, 0x3fb8aa3b, v111
	v_exp_f32_e32 v110, v110
	v_exp_f32_e32 v111, v111
	v_add_f32_e32 v110, 1.0, v110
	v_add_f32_e32 v111, 1.0, v111
	v_rcp_f32_e32 v110, v110
	v_rcp_f32_e32 v111, v111
	s_nop 0
	v_pk_mul_f32 v[106:107], v[106:107], v[110:111]
	v_mul_f32_e32 v110, 0x3d372713, v108
	v_mul_f32_e32 v111, 0x3d372713, v109
	v_mul_f32_e32 v110, v108, v110
	v_mul_f32_e32 v111, v109, v111
	v_fma_f32 v110, v108, v110, v108
	v_fma_f32 v111, v109, v111, v109
	v_mul_f32_e32 v110, 0xbfcc422a, v110
	v_mul_f32_e32 v111, 0xbfcc422a, v111
	v_mul_f32_e32 v110, 0x3fb8aa3b, v110
	v_mul_f32_e32 v111, 0x3fb8aa3b, v111
	v_exp_f32_e32 v110, v110
	v_exp_f32_e32 v111, v111
	v_cvt_pk_bf16_f32 v234, v106, v107
	v_add_f32_e32 v110, 1.0, v110
	v_add_f32_e32 v111, 1.0, v111
	v_rcp_f32_e32 v110, v110
	v_rcp_f32_e32 v111, v111
	s_nop 0
	v_pk_mul_f32 v[108:109], v[108:109], v[110:111]
	s_nop 0
	v_cvt_pk_bf16_f32 v235, v108, v109
	v_mul_f32_e32 v106, 0x3d372713, v102
	v_mul_f32_e32 v107, 0x3d372713, v103
	v_mul_f32_e32 v106, v102, v106
	v_mul_f32_e32 v107, v103, v107
	v_fma_f32 v106, v102, v106, v102
	v_fma_f32 v107, v103, v107, v103
	v_mul_f32_e32 v106, 0xbfcc422a, v106
	v_mul_f32_e32 v107, 0xbfcc422a, v107
	v_mul_f32_e32 v106, 0x3fb8aa3b, v106
	v_mul_f32_e32 v107, 0x3fb8aa3b, v107
	v_exp_f32_e32 v106, v106
	v_exp_f32_e32 v107, v107
	v_add_f32_e32 v106, 1.0, v106
	v_add_f32_e32 v107, 1.0, v107
	v_rcp_f32_e32 v106, v106
	v_rcp_f32_e32 v107, v107
	s_nop 0
	v_pk_mul_f32 v[102:103], v[102:103], v[106:107]
	v_mul_f32_e32 v106, 0x3d372713, v104
	v_mul_f32_e32 v107, 0x3d372713, v105
	v_mul_f32_e32 v106, v104, v106
	v_mul_f32_e32 v107, v105, v107
	v_fma_f32 v106, v104, v106, v104
	v_fma_f32 v107, v105, v107, v105
	v_mul_f32_e32 v106, 0xbfcc422a, v106
	v_mul_f32_e32 v107, 0xbfcc422a, v107
	v_mul_f32_e32 v106, 0x3fb8aa3b, v106
	v_mul_f32_e32 v107, 0x3fb8aa3b, v107
	v_exp_f32_e32 v106, v106
	v_exp_f32_e32 v107, v107
	v_cvt_pk_bf16_f32 v236, v102, v103
	v_add_f32_e32 v106, 1.0, v106
	v_add_f32_e32 v107, 1.0, v107
	v_rcp_f32_e32 v106, v106
	v_rcp_f32_e32 v107, v107
	s_nop 0
	v_pk_mul_f32 v[104:105], v[104:105], v[106:107]
	s_nop 0
	v_cvt_pk_bf16_f32 v237, v104, v105
	v_mul_f32_e32 v102, 0x3d372713, v98
	v_mul_f32_e32 v103, 0x3d372713, v99
	v_mul_f32_e32 v102, v98, v102
	v_mul_f32_e32 v103, v99, v103
	v_fma_f32 v102, v98, v102, v98
	v_fma_f32 v103, v99, v103, v99
	v_mul_f32_e32 v102, 0xbfcc422a, v102
	v_mul_f32_e32 v103, 0xbfcc422a, v103
	v_mul_f32_e32 v102, 0x3fb8aa3b, v102
	v_mul_f32_e32 v103, 0x3fb8aa3b, v103
	v_exp_f32_e32 v102, v102
	v_exp_f32_e32 v103, v103
	v_add_f32_e32 v102, 1.0, v102
	v_add_f32_e32 v103, 1.0, v103
	v_rcp_f32_e32 v102, v102
	v_rcp_f32_e32 v103, v103
	s_nop 0
	v_pk_mul_f32 v[98:99], v[98:99], v[102:103]
	v_mul_f32_e32 v102, 0x3d372713, v100
	v_mul_f32_e32 v103, 0x3d372713, v101
	v_mul_f32_e32 v102, v100, v102
	v_mul_f32_e32 v103, v101, v103
	v_fma_f32 v102, v100, v102, v100
	v_fma_f32 v103, v101, v103, v101
	v_mul_f32_e32 v102, 0xbfcc422a, v102
	v_mul_f32_e32 v103, 0xbfcc422a, v103
	v_mul_f32_e32 v102, 0x3fb8aa3b, v102
	v_mul_f32_e32 v103, 0x3fb8aa3b, v103
	v_exp_f32_e32 v102, v102
	v_exp_f32_e32 v103, v103
	v_cvt_pk_bf16_f32 v238, v98, v99
	v_add_f32_e32 v102, 1.0, v102
	v_add_f32_e32 v103, 1.0, v103
	v_rcp_f32_e32 v102, v102
	v_rcp_f32_e32 v103, v103
	s_nop 0
	v_pk_mul_f32 v[100:101], v[100:101], v[102:103]
	s_nop 0
	v_cvt_pk_bf16_f32 v239, v100, v101
	s_nop 1
	v_permlane16_swap_b32_e32 v232, v234
	v_permlane16_swap_b32_e32 v233, v235
	v_permlane16_swap_b32_e32 v236, v238
	v_permlane16_swap_b32_e32 v237, v239
	v_lshl_add_u64 v[240:241], v[126:127], 0, v[244:245]
	global_store_dwordx4 v[240:241], v[232:235], off offset:256
	global_store_dwordx4 v[240:241], v[236:239], off offset:320
	v_mul_f32_e32 v98, 0x3d372713, v94
	v_mul_f32_e32 v99, 0x3d372713, v95
	v_mul_f32_e32 v98, v94, v98
	v_mul_f32_e32 v99, v95, v99
	v_fma_f32 v98, v94, v98, v94
	v_fma_f32 v99, v95, v99, v95
	v_mul_f32_e32 v98, 0xbfcc422a, v98
	v_mul_f32_e32 v99, 0xbfcc422a, v99
	v_mul_f32_e32 v98, 0x3fb8aa3b, v98
	v_mul_f32_e32 v99, 0x3fb8aa3b, v99
	v_exp_f32_e32 v98, v98
	v_exp_f32_e32 v99, v99
	v_add_f32_e32 v98, 1.0, v98
	v_add_f32_e32 v99, 1.0, v99
	v_rcp_f32_e32 v98, v98
	v_rcp_f32_e32 v99, v99
	s_nop 0
	v_pk_mul_f32 v[94:95], v[94:95], v[98:99]
	v_mul_f32_e32 v98, 0x3d372713, v96
	v_mul_f32_e32 v99, 0x3d372713, v97
	v_mul_f32_e32 v98, v96, v98
	v_mul_f32_e32 v99, v97, v99
	v_fma_f32 v98, v96, v98, v96
	v_fma_f32 v99, v97, v99, v97
	v_mul_f32_e32 v98, 0xbfcc422a, v98
	v_mul_f32_e32 v99, 0xbfcc422a, v99
	v_mul_f32_e32 v98, 0x3fb8aa3b, v98
	v_mul_f32_e32 v99, 0x3fb8aa3b, v99
	v_exp_f32_e32 v98, v98
	v_exp_f32_e32 v99, v99
	v_add_f32_e32 v98, 1.0, v98
	v_add_f32_e32 v99, 1.0, v99
	v_rcp_f32_e32 v98, v98
	v_rcp_f32_e32 v99, v99
	s_nop 0
	v_pk_mul_f32 v[96:97], v[96:97], v[98:99]
	s_nop 0
	v_cvt_pk_bf16_f32 v179, v96, v97
	v_add_co_u32_e32 v96, vcc, s0, v126
	v_cvt_pk_bf16_f32 v178, v94, v95
	s_nop 0
	v_addc_co_u32_e32 v97, vcc, 0, v127, vcc
	v_mul_f32_e32 v96, 0x3d372713, v90
	v_mul_f32_e32 v97, 0x3d372713, v91
	v_mul_f32_e32 v96, v90, v96
	v_mul_f32_e32 v97, v91, v97
	v_fma_f32 v96, v90, v96, v90
	v_fma_f32 v97, v91, v97, v91
	v_mul_f32_e32 v96, 0xbfcc422a, v96
	v_mul_f32_e32 v97, 0xbfcc422a, v97
	v_mul_f32_e32 v96, 0x3fb8aa3b, v96
	v_mul_f32_e32 v97, 0x3fb8aa3b, v97
	v_exp_f32_e32 v96, v96
	v_exp_f32_e32 v97, v97
	v_lshl_add_u64 v[94:95], v[126:127], 0, s[8:9]
	s_mov_b32 s0, 0x20000
	v_add_f32_e32 v96, 1.0, v96
	v_add_f32_e32 v97, 1.0, v97
	v_rcp_f32_e32 v96, v96
	v_rcp_f32_e32 v97, v97
	s_mov_b64 s[8:9], 0x20000
	v_pk_mul_f32 v[90:91], v[90:91], v[96:97]
	v_mul_f32_e32 v96, 0x3d372713, v92
	v_mul_f32_e32 v97, 0x3d372713, v93
	v_mul_f32_e32 v96, v92, v96
	v_mul_f32_e32 v97, v93, v97
	v_fma_f32 v96, v92, v96, v92
	v_fma_f32 v97, v93, v97, v93
	v_mul_f32_e32 v96, 0xbfcc422a, v96
	v_mul_f32_e32 v97, 0xbfcc422a, v97
	v_mul_f32_e32 v96, 0x3fb8aa3b, v96
	v_mul_f32_e32 v97, 0x3fb8aa3b, v97
	v_exp_f32_e32 v96, v96
	v_exp_f32_e32 v97, v97
	v_cvt_pk_bf16_f32 v180, v90, v91
	v_add_f32_e32 v96, 1.0, v96
	v_add_f32_e32 v97, 1.0, v97
	v_rcp_f32_e32 v96, v96
	v_rcp_f32_e32 v97, v97
	s_nop 0
	v_pk_mul_f32 v[92:93], v[92:93], v[96:97]
	s_nop 0
	v_cvt_pk_bf16_f32 v181, v92, v93
	v_mul_f32_e32 v90, 0x3d372713, v86
	v_mul_f32_e32 v91, 0x3d372713, v87
	v_mul_f32_e32 v90, v86, v90
	v_mul_f32_e32 v91, v87, v91
	v_fma_f32 v90, v86, v90, v86
	v_fma_f32 v91, v87, v91, v87
	v_mul_f32_e32 v90, 0xbfcc422a, v90
	v_mul_f32_e32 v91, 0xbfcc422a, v91
	v_mul_f32_e32 v90, 0x3fb8aa3b, v90
	v_mul_f32_e32 v91, 0x3fb8aa3b, v91
	v_exp_f32_e32 v90, v90
	v_exp_f32_e32 v91, v91
	v_add_f32_e32 v90, 1.0, v90
	v_add_f32_e32 v91, 1.0, v91
	v_rcp_f32_e32 v90, v90
	v_rcp_f32_e32 v91, v91
	s_nop 0
	v_pk_mul_f32 v[86:87], v[86:87], v[90:91]
	v_mul_f32_e32 v90, 0x3d372713, v88
	v_mul_f32_e32 v91, 0x3d372713, v89
	v_mul_f32_e32 v90, v88, v90
	v_mul_f32_e32 v91, v89, v91
	v_fma_f32 v90, v88, v90, v88
	v_fma_f32 v91, v89, v91, v89
	v_mul_f32_e32 v90, 0xbfcc422a, v90
	v_mul_f32_e32 v91, 0xbfcc422a, v91
	v_mul_f32_e32 v90, 0x3fb8aa3b, v90
	v_mul_f32_e32 v91, 0x3fb8aa3b, v91
	v_exp_f32_e32 v90, v90
	v_exp_f32_e32 v91, v91
	v_cvt_pk_bf16_f32 v182, v86, v87
	v_add_f32_e32 v90, 1.0, v90
	v_add_f32_e32 v91, 1.0, v91
	v_rcp_f32_e32 v90, v90
	v_rcp_f32_e32 v91, v91
	s_nop 0
	v_pk_mul_f32 v[88:89], v[88:89], v[90:91]
	s_nop 0
	v_cvt_pk_bf16_f32 v183, v88, v89
	v_mul_f32_e32 v86, 0x3d372713, v82
	v_mul_f32_e32 v87, 0x3d372713, v83
	v_mul_f32_e32 v86, v82, v86
	v_mul_f32_e32 v87, v83, v87
	v_fma_f32 v86, v82, v86, v82
	v_fma_f32 v87, v83, v87, v83
	v_mul_f32_e32 v86, 0xbfcc422a, v86
	v_mul_f32_e32 v87, 0xbfcc422a, v87
	v_mul_f32_e32 v86, 0x3fb8aa3b, v86
	v_mul_f32_e32 v87, 0x3fb8aa3b, v87
	v_exp_f32_e32 v86, v86
	v_exp_f32_e32 v87, v87
	v_add_f32_e32 v86, 1.0, v86
	v_add_f32_e32 v87, 1.0, v87
	v_rcp_f32_e32 v86, v86
	v_rcp_f32_e32 v87, v87
	s_nop 0
	v_pk_mul_f32 v[82:83], v[82:83], v[86:87]
	v_mul_f32_e32 v86, 0x3d372713, v84
	v_mul_f32_e32 v87, 0x3d372713, v85
	v_mul_f32_e32 v86, v84, v86
	v_mul_f32_e32 v87, v85, v87
	v_fma_f32 v86, v84, v86, v84
	v_fma_f32 v87, v85, v87, v85
	v_mul_f32_e32 v86, 0xbfcc422a, v86
	v_mul_f32_e32 v87, 0xbfcc422a, v87
	v_mul_f32_e32 v86, 0x3fb8aa3b, v86
	v_mul_f32_e32 v87, 0x3fb8aa3b, v87
	v_exp_f32_e32 v86, v86
	v_exp_f32_e32 v87, v87
	v_cvt_pk_bf16_f32 v184, v82, v83
	v_add_f32_e32 v86, 1.0, v86
	v_add_f32_e32 v87, 1.0, v87
	v_rcp_f32_e32 v86, v86
	v_rcp_f32_e32 v87, v87
	s_nop 0
	v_pk_mul_f32 v[84:85], v[84:85], v[86:87]
	s_nop 0
	v_cvt_pk_bf16_f32 v185, v84, v85
	s_nop 1
	v_permlane16_swap_b32_e32 v178, v180
	v_permlane16_swap_b32_e32 v179, v181
	v_permlane16_swap_b32_e32 v182, v184
	v_permlane16_swap_b32_e32 v183, v185
	v_lshl_add_u64 v[240:241], v[94:95], 0, v[244:245]
	global_store_dwordx4 v[240:241], v[178:181], off
	global_store_dwordx4 v[240:241], v[182:185], off offset:64
	v_mul_f32_e32 v82, 0x3d372713, v78
	v_mul_f32_e32 v83, 0x3d372713, v79
	v_mul_f32_e32 v82, v78, v82
	v_mul_f32_e32 v83, v79, v83
	v_fma_f32 v82, v78, v82, v78
	v_fma_f32 v83, v79, v83, v79
	v_mul_f32_e32 v82, 0xbfcc422a, v82
	v_mul_f32_e32 v83, 0xbfcc422a, v83
	v_mul_f32_e32 v82, 0x3fb8aa3b, v82
	v_mul_f32_e32 v83, 0x3fb8aa3b, v83
	v_exp_f32_e32 v82, v82
	v_exp_f32_e32 v83, v83
	v_add_f32_e32 v82, 1.0, v82
	v_add_f32_e32 v83, 1.0, v83
	v_rcp_f32_e32 v82, v82
	v_rcp_f32_e32 v83, v83
	s_nop 0
	v_pk_mul_f32 v[78:79], v[78:79], v[82:83]
	v_mul_f32_e32 v82, 0x3d372713, v80
	v_mul_f32_e32 v83, 0x3d372713, v81
	v_mul_f32_e32 v82, v80, v82
	v_mul_f32_e32 v83, v81, v83
	v_fma_f32 v82, v80, v82, v80
	v_fma_f32 v83, v81, v83, v81
	v_mul_f32_e32 v82, 0xbfcc422a, v82
	v_mul_f32_e32 v83, 0xbfcc422a, v83
	v_mul_f32_e32 v82, 0x3fb8aa3b, v82
	v_mul_f32_e32 v83, 0x3fb8aa3b, v83
	v_exp_f32_e32 v82, v82
	v_exp_f32_e32 v83, v83
	v_cvt_pk_bf16_f32 v186, v78, v79
	v_add_f32_e32 v82, 1.0, v82
	v_add_f32_e32 v83, 1.0, v83
	v_rcp_f32_e32 v82, v82
	v_rcp_f32_e32 v83, v83
	s_nop 0
	v_pk_mul_f32 v[80:81], v[80:81], v[82:83]
	s_nop 0
	v_cvt_pk_bf16_f32 v187, v80, v81
	v_mul_f32_e32 v78, 0x3d372713, v74
	v_mul_f32_e32 v79, 0x3d372713, v75
	v_mul_f32_e32 v78, v74, v78
	v_mul_f32_e32 v79, v75, v79
	v_fma_f32 v78, v74, v78, v74
	v_fma_f32 v79, v75, v79, v75
	v_mul_f32_e32 v78, 0xbfcc422a, v78
	v_mul_f32_e32 v79, 0xbfcc422a, v79
	v_mul_f32_e32 v78, 0x3fb8aa3b, v78
	v_mul_f32_e32 v79, 0x3fb8aa3b, v79
	v_exp_f32_e32 v78, v78
	v_exp_f32_e32 v79, v79
	v_add_f32_e32 v78, 1.0, v78
	v_add_f32_e32 v79, 1.0, v79
	v_rcp_f32_e32 v78, v78
	v_rcp_f32_e32 v79, v79
	s_nop 0
	v_pk_mul_f32 v[74:75], v[74:75], v[78:79]
	v_mul_f32_e32 v78, 0x3d372713, v76
	v_mul_f32_e32 v79, 0x3d372713, v77
	v_mul_f32_e32 v78, v76, v78
	v_mul_f32_e32 v79, v77, v79
	v_fma_f32 v78, v76, v78, v76
	v_fma_f32 v79, v77, v79, v77
	v_mul_f32_e32 v78, 0xbfcc422a, v78
	v_mul_f32_e32 v79, 0xbfcc422a, v79
	v_mul_f32_e32 v78, 0x3fb8aa3b, v78
	v_mul_f32_e32 v79, 0x3fb8aa3b, v79
	v_exp_f32_e32 v78, v78
	v_exp_f32_e32 v79, v79
	v_cvt_pk_bf16_f32 v188, v74, v75
	v_add_f32_e32 v78, 1.0, v78
	v_add_f32_e32 v79, 1.0, v79
	v_rcp_f32_e32 v78, v78
	v_rcp_f32_e32 v79, v79
	s_nop 0
	v_pk_mul_f32 v[76:77], v[76:77], v[78:79]
	s_nop 0
	v_cvt_pk_bf16_f32 v189, v76, v77
	v_mul_f32_e32 v74, 0x3d372713, v70
	v_mul_f32_e32 v75, 0x3d372713, v71
	v_mul_f32_e32 v74, v70, v74
	v_mul_f32_e32 v75, v71, v75
	v_fma_f32 v74, v70, v74, v70
	v_fma_f32 v75, v71, v75, v71
	v_mul_f32_e32 v74, 0xbfcc422a, v74
	v_mul_f32_e32 v75, 0xbfcc422a, v75
	v_mul_f32_e32 v74, 0x3fb8aa3b, v74
	v_mul_f32_e32 v75, 0x3fb8aa3b, v75
	v_exp_f32_e32 v74, v74
	v_exp_f32_e32 v75, v75
	v_add_f32_e32 v74, 1.0, v74
	v_add_f32_e32 v75, 1.0, v75
	v_rcp_f32_e32 v74, v74
	v_rcp_f32_e32 v75, v75
	s_nop 0
	v_pk_mul_f32 v[70:71], v[70:71], v[74:75]
	v_mul_f32_e32 v74, 0x3d372713, v72
	v_mul_f32_e32 v75, 0x3d372713, v73
	v_mul_f32_e32 v74, v72, v74
	v_mul_f32_e32 v75, v73, v75
	v_fma_f32 v74, v72, v74, v72
	v_fma_f32 v75, v73, v75, v73
	v_mul_f32_e32 v74, 0xbfcc422a, v74
	v_mul_f32_e32 v75, 0xbfcc422a, v75
	v_mul_f32_e32 v74, 0x3fb8aa3b, v74
	v_mul_f32_e32 v75, 0x3fb8aa3b, v75
	v_exp_f32_e32 v74, v74
	v_exp_f32_e32 v75, v75
	v_cvt_pk_bf16_f32 v190, v70, v71
	v_add_f32_e32 v74, 1.0, v74
	v_add_f32_e32 v75, 1.0, v75
	v_rcp_f32_e32 v74, v74
	v_rcp_f32_e32 v75, v75
	s_nop 0
	v_pk_mul_f32 v[72:73], v[72:73], v[74:75]
	s_nop 0
	v_cvt_pk_bf16_f32 v191, v72, v73
	v_mul_f32_e32 v70, 0x3d372713, v66
	v_mul_f32_e32 v71, 0x3d372713, v67
	v_mul_f32_e32 v70, v66, v70
	v_mul_f32_e32 v71, v67, v71
	v_fma_f32 v70, v66, v70, v66
	v_fma_f32 v71, v67, v71, v67
	v_mul_f32_e32 v70, 0xbfcc422a, v70
	v_mul_f32_e32 v71, 0xbfcc422a, v71
	v_mul_f32_e32 v70, 0x3fb8aa3b, v70
	v_mul_f32_e32 v71, 0x3fb8aa3b, v71
	v_exp_f32_e32 v70, v70
	v_exp_f32_e32 v71, v71
	v_add_f32_e32 v70, 1.0, v70
	v_add_f32_e32 v71, 1.0, v71
	v_rcp_f32_e32 v70, v70
	v_rcp_f32_e32 v71, v71
	s_nop 0
	v_pk_mul_f32 v[66:67], v[66:67], v[70:71]
	v_mul_f32_e32 v70, 0x3d372713, v68
	v_mul_f32_e32 v71, 0x3d372713, v69
	v_mul_f32_e32 v70, v68, v70
	v_mul_f32_e32 v71, v69, v71
	v_fma_f32 v70, v68, v70, v68
	v_fma_f32 v71, v69, v71, v69
	v_mul_f32_e32 v70, 0xbfcc422a, v70
	v_mul_f32_e32 v71, 0xbfcc422a, v71
	v_mul_f32_e32 v70, 0x3fb8aa3b, v70
	v_mul_f32_e32 v71, 0x3fb8aa3b, v71
	v_exp_f32_e32 v70, v70
	v_exp_f32_e32 v71, v71
	v_cvt_pk_bf16_f32 v192, v66, v67
	v_add_f32_e32 v70, 1.0, v70
	v_add_f32_e32 v71, 1.0, v71
	v_rcp_f32_e32 v70, v70
	v_rcp_f32_e32 v71, v71
	s_nop 0
	v_pk_mul_f32 v[68:69], v[68:69], v[70:71]
	s_nop 0
	v_cvt_pk_bf16_f32 v193, v68, v69
	s_nop 1
	v_permlane16_swap_b32_e32 v186, v188
	v_permlane16_swap_b32_e32 v187, v189
	v_permlane16_swap_b32_e32 v190, v192
	v_permlane16_swap_b32_e32 v191, v193
	v_lshl_add_u64 v[240:241], v[94:95], 0, v[244:245]
	global_store_dwordx4 v[240:241], v[186:189], off offset:256
	global_store_dwordx4 v[240:241], v[190:193], off offset:320
	v_mul_f32_e32 v66, 0x3d372713, v62
	v_mul_f32_e32 v67, 0x3d372713, v63
	v_mul_f32_e32 v66, v62, v66
	v_mul_f32_e32 v67, v63, v67
	v_fma_f32 v66, v62, v66, v62
	v_fma_f32 v67, v63, v67, v63
	v_mul_f32_e32 v66, 0xbfcc422a, v66
	v_mul_f32_e32 v67, 0xbfcc422a, v67
	v_mul_f32_e32 v66, 0x3fb8aa3b, v66
	v_mul_f32_e32 v67, 0x3fb8aa3b, v67
	v_exp_f32_e32 v66, v66
	v_exp_f32_e32 v67, v67
	v_add_f32_e32 v66, 1.0, v66
	v_add_f32_e32 v67, 1.0, v67
	v_rcp_f32_e32 v66, v66
	v_rcp_f32_e32 v67, v67
	s_nop 0
	v_pk_mul_f32 v[62:63], v[62:63], v[66:67]
	v_mul_f32_e32 v66, 0x3d372713, v64
	v_mul_f32_e32 v67, 0x3d372713, v65
	v_mul_f32_e32 v66, v64, v66
	v_mul_f32_e32 v67, v65, v67
	v_fma_f32 v66, v64, v66, v64
	v_fma_f32 v67, v65, v67, v65
	v_mul_f32_e32 v66, 0xbfcc422a, v66
	v_mul_f32_e32 v67, 0xbfcc422a, v67
	v_mul_f32_e32 v66, 0x3fb8aa3b, v66
	v_mul_f32_e32 v67, 0x3fb8aa3b, v67
	v_exp_f32_e32 v66, v66
	v_exp_f32_e32 v67, v67
	v_add_f32_e32 v66, 1.0, v66
	v_add_f32_e32 v67, 1.0, v67
	v_rcp_f32_e32 v66, v66
	v_rcp_f32_e32 v67, v67
	s_nop 0
	v_pk_mul_f32 v[64:65], v[64:65], v[66:67]
	s_nop 0
	v_cvt_pk_bf16_f32 v195, v64, v65
	v_add_co_u32_e32 v64, vcc, s0, v126
	v_cvt_pk_bf16_f32 v194, v62, v63
	s_nop 0
	v_addc_co_u32_e32 v65, vcc, 0, v127, vcc
	v_mul_f32_e32 v64, 0x3d372713, v58
	v_mul_f32_e32 v65, 0x3d372713, v59
	v_mul_f32_e32 v64, v58, v64
	v_mul_f32_e32 v65, v59, v65
	v_fma_f32 v64, v58, v64, v58
	v_fma_f32 v65, v59, v65, v59
	v_mul_f32_e32 v64, 0xbfcc422a, v64
	v_mul_f32_e32 v65, 0xbfcc422a, v65
	v_mul_f32_e32 v64, 0x3fb8aa3b, v64
	v_mul_f32_e32 v65, 0x3fb8aa3b, v65
	v_exp_f32_e32 v64, v64
	v_exp_f32_e32 v65, v65
	v_lshl_add_u64 v[62:63], v[126:127], 0, s[8:9]
	s_mov_b32 s0, 0x24000
	v_add_f32_e32 v64, 1.0, v64
	v_add_f32_e32 v65, 1.0, v65
	v_rcp_f32_e32 v64, v64
	v_rcp_f32_e32 v65, v65
	s_mov_b64 s[8:9], 0x24000
	v_pk_mul_f32 v[58:59], v[58:59], v[64:65]
	v_mul_f32_e32 v64, 0x3d372713, v60
	v_mul_f32_e32 v65, 0x3d372713, v61
	v_mul_f32_e32 v64, v60, v64
	v_mul_f32_e32 v65, v61, v65
	v_fma_f32 v64, v60, v64, v60
	v_fma_f32 v65, v61, v65, v61
	v_mul_f32_e32 v64, 0xbfcc422a, v64
	v_mul_f32_e32 v65, 0xbfcc422a, v65
	v_mul_f32_e32 v64, 0x3fb8aa3b, v64
	v_mul_f32_e32 v65, 0x3fb8aa3b, v65
	v_exp_f32_e32 v64, v64
	v_exp_f32_e32 v65, v65
	v_cvt_pk_bf16_f32 v196, v58, v59
	v_add_f32_e32 v64, 1.0, v64
	v_add_f32_e32 v65, 1.0, v65
	v_rcp_f32_e32 v64, v64
	v_rcp_f32_e32 v65, v65
	s_nop 0
	v_pk_mul_f32 v[60:61], v[60:61], v[64:65]
	s_nop 0
	v_cvt_pk_bf16_f32 v197, v60, v61
	v_mul_f32_e32 v58, 0x3d372713, v54
	v_mul_f32_e32 v59, 0x3d372713, v55
	v_mul_f32_e32 v58, v54, v58
	v_mul_f32_e32 v59, v55, v59
	v_fma_f32 v58, v54, v58, v54
	v_fma_f32 v59, v55, v59, v55
	v_mul_f32_e32 v58, 0xbfcc422a, v58
	v_mul_f32_e32 v59, 0xbfcc422a, v59
	v_mul_f32_e32 v58, 0x3fb8aa3b, v58
	v_mul_f32_e32 v59, 0x3fb8aa3b, v59
	v_exp_f32_e32 v58, v58
	v_exp_f32_e32 v59, v59
	v_add_f32_e32 v58, 1.0, v58
	v_add_f32_e32 v59, 1.0, v59
	v_rcp_f32_e32 v58, v58
	v_rcp_f32_e32 v59, v59
	s_nop 0
	v_pk_mul_f32 v[54:55], v[54:55], v[58:59]
	v_mul_f32_e32 v58, 0x3d372713, v56
	v_mul_f32_e32 v59, 0x3d372713, v57
	v_mul_f32_e32 v58, v56, v58
	v_mul_f32_e32 v59, v57, v59
	v_fma_f32 v58, v56, v58, v56
	v_fma_f32 v59, v57, v59, v57
	v_mul_f32_e32 v58, 0xbfcc422a, v58
	v_mul_f32_e32 v59, 0xbfcc422a, v59
	v_mul_f32_e32 v58, 0x3fb8aa3b, v58
	v_mul_f32_e32 v59, 0x3fb8aa3b, v59
	v_exp_f32_e32 v58, v58
	v_exp_f32_e32 v59, v59
	v_cvt_pk_bf16_f32 v198, v54, v55
	v_add_f32_e32 v58, 1.0, v58
	v_add_f32_e32 v59, 1.0, v59
	v_rcp_f32_e32 v58, v58
	v_rcp_f32_e32 v59, v59
	s_nop 0
	v_pk_mul_f32 v[56:57], v[56:57], v[58:59]
	s_nop 0
	v_cvt_pk_bf16_f32 v199, v56, v57
	v_mul_f32_e32 v54, 0x3d372713, v50
	v_mul_f32_e32 v55, 0x3d372713, v51
	v_mul_f32_e32 v54, v50, v54
	v_mul_f32_e32 v55, v51, v55
	v_fma_f32 v54, v50, v54, v50
	v_fma_f32 v55, v51, v55, v51
	v_mul_f32_e32 v54, 0xbfcc422a, v54
	v_mul_f32_e32 v55, 0xbfcc422a, v55
	v_mul_f32_e32 v54, 0x3fb8aa3b, v54
	v_mul_f32_e32 v55, 0x3fb8aa3b, v55
	v_exp_f32_e32 v54, v54
	v_exp_f32_e32 v55, v55
	v_add_f32_e32 v54, 1.0, v54
	v_add_f32_e32 v55, 1.0, v55
	v_rcp_f32_e32 v54, v54
	v_rcp_f32_e32 v55, v55
	s_nop 0
	v_pk_mul_f32 v[50:51], v[50:51], v[54:55]
	v_mul_f32_e32 v54, 0x3d372713, v52
	v_mul_f32_e32 v55, 0x3d372713, v53
	v_mul_f32_e32 v54, v52, v54
	v_mul_f32_e32 v55, v53, v55
	v_fma_f32 v54, v52, v54, v52
	v_fma_f32 v55, v53, v55, v53
	v_mul_f32_e32 v54, 0xbfcc422a, v54
	v_mul_f32_e32 v55, 0xbfcc422a, v55
	v_mul_f32_e32 v54, 0x3fb8aa3b, v54
	v_mul_f32_e32 v55, 0x3fb8aa3b, v55
	v_exp_f32_e32 v54, v54
	v_exp_f32_e32 v55, v55
	v_cvt_pk_bf16_f32 v200, v50, v51
	v_add_f32_e32 v54, 1.0, v54
	v_add_f32_e32 v55, 1.0, v55
	v_rcp_f32_e32 v54, v54
	v_rcp_f32_e32 v55, v55
	s_nop 0
	v_pk_mul_f32 v[52:53], v[52:53], v[54:55]
	s_nop 0
	v_cvt_pk_bf16_f32 v201, v52, v53
	s_nop 1
	v_permlane16_swap_b32_e32 v194, v196
	v_permlane16_swap_b32_e32 v195, v197
	v_permlane16_swap_b32_e32 v198, v200
	v_permlane16_swap_b32_e32 v199, v201
	v_lshl_add_u64 v[240:241], v[62:63], 0, v[244:245]
	global_store_dwordx4 v[240:241], v[194:197], off
	global_store_dwordx4 v[240:241], v[198:201], off offset:64
	v_mul_f32_e32 v50, 0x3d372713, v46
	v_mul_f32_e32 v51, 0x3d372713, v47
	v_mul_f32_e32 v50, v46, v50
	v_mul_f32_e32 v51, v47, v51
	v_fma_f32 v50, v46, v50, v46
	v_fma_f32 v51, v47, v51, v47
	v_mul_f32_e32 v50, 0xbfcc422a, v50
	v_mul_f32_e32 v51, 0xbfcc422a, v51
	v_mul_f32_e32 v50, 0x3fb8aa3b, v50
	v_mul_f32_e32 v51, 0x3fb8aa3b, v51
	v_exp_f32_e32 v50, v50
	v_exp_f32_e32 v51, v51
	v_add_f32_e32 v50, 1.0, v50
	v_add_f32_e32 v51, 1.0, v51
	v_rcp_f32_e32 v50, v50
	v_rcp_f32_e32 v51, v51
	s_nop 0
	v_pk_mul_f32 v[46:47], v[46:47], v[50:51]
	v_mul_f32_e32 v50, 0x3d372713, v48
	v_mul_f32_e32 v51, 0x3d372713, v49
	v_mul_f32_e32 v50, v48, v50
	v_mul_f32_e32 v51, v49, v51
	v_fma_f32 v50, v48, v50, v48
	v_fma_f32 v51, v49, v51, v49
	v_mul_f32_e32 v50, 0xbfcc422a, v50
	v_mul_f32_e32 v51, 0xbfcc422a, v51
	v_mul_f32_e32 v50, 0x3fb8aa3b, v50
	v_mul_f32_e32 v51, 0x3fb8aa3b, v51
	v_exp_f32_e32 v50, v50
	v_exp_f32_e32 v51, v51
	v_cvt_pk_bf16_f32 v224, v46, v47
	v_add_f32_e32 v50, 1.0, v50
	v_add_f32_e32 v51, 1.0, v51
	v_rcp_f32_e32 v50, v50
	v_rcp_f32_e32 v51, v51
	s_nop 0
	v_pk_mul_f32 v[48:49], v[48:49], v[50:51]
	s_nop 0
	v_cvt_pk_bf16_f32 v225, v48, v49
	v_mul_f32_e32 v46, 0x3d372713, v42
	v_mul_f32_e32 v47, 0x3d372713, v43
	v_mul_f32_e32 v46, v42, v46
	v_mul_f32_e32 v47, v43, v47
	v_fma_f32 v46, v42, v46, v42
	v_fma_f32 v47, v43, v47, v43
	v_mul_f32_e32 v46, 0xbfcc422a, v46
	v_mul_f32_e32 v47, 0xbfcc422a, v47
	v_mul_f32_e32 v46, 0x3fb8aa3b, v46
	v_mul_f32_e32 v47, 0x3fb8aa3b, v47
	v_exp_f32_e32 v46, v46
	v_exp_f32_e32 v47, v47
	v_add_f32_e32 v46, 1.0, v46
	v_add_f32_e32 v47, 1.0, v47
	v_rcp_f32_e32 v46, v46
	v_rcp_f32_e32 v47, v47
	s_nop 0
	v_pk_mul_f32 v[42:43], v[42:43], v[46:47]
	v_mul_f32_e32 v46, 0x3d372713, v44
	v_mul_f32_e32 v47, 0x3d372713, v45
	v_mul_f32_e32 v46, v44, v46
	v_mul_f32_e32 v47, v45, v47
	v_fma_f32 v46, v44, v46, v44
	v_fma_f32 v47, v45, v47, v45
	v_mul_f32_e32 v46, 0xbfcc422a, v46
	v_mul_f32_e32 v47, 0xbfcc422a, v47
	v_mul_f32_e32 v46, 0x3fb8aa3b, v46
	v_mul_f32_e32 v47, 0x3fb8aa3b, v47
	v_exp_f32_e32 v46, v46
	v_exp_f32_e32 v47, v47
	v_cvt_pk_bf16_f32 v226, v42, v43
	v_add_f32_e32 v46, 1.0, v46
	v_add_f32_e32 v47, 1.0, v47
	v_rcp_f32_e32 v46, v46
	v_rcp_f32_e32 v47, v47
	s_nop 0
	v_pk_mul_f32 v[44:45], v[44:45], v[46:47]
	s_nop 0
	v_cvt_pk_bf16_f32 v227, v44, v45
	v_mul_f32_e32 v42, 0x3d372713, v38
	v_mul_f32_e32 v43, 0x3d372713, v39
	v_mul_f32_e32 v42, v38, v42
	v_mul_f32_e32 v43, v39, v43
	v_fma_f32 v42, v38, v42, v38
	v_fma_f32 v43, v39, v43, v39
	v_mul_f32_e32 v42, 0xbfcc422a, v42
	v_mul_f32_e32 v43, 0xbfcc422a, v43
	v_mul_f32_e32 v42, 0x3fb8aa3b, v42
	v_mul_f32_e32 v43, 0x3fb8aa3b, v43
	v_exp_f32_e32 v42, v42
	v_exp_f32_e32 v43, v43
	v_add_f32_e32 v42, 1.0, v42
	v_add_f32_e32 v43, 1.0, v43
	v_rcp_f32_e32 v42, v42
	v_rcp_f32_e32 v43, v43
	s_nop 0
	v_pk_mul_f32 v[38:39], v[38:39], v[42:43]
	v_mul_f32_e32 v42, 0x3d372713, v40
	v_mul_f32_e32 v43, 0x3d372713, v41
	v_mul_f32_e32 v42, v40, v42
	v_mul_f32_e32 v43, v41, v43
	v_fma_f32 v42, v40, v42, v40
	v_fma_f32 v43, v41, v43, v41
	v_mul_f32_e32 v42, 0xbfcc422a, v42
	v_mul_f32_e32 v43, 0xbfcc422a, v43
	v_mul_f32_e32 v42, 0x3fb8aa3b, v42
	v_mul_f32_e32 v43, 0x3fb8aa3b, v43
	v_exp_f32_e32 v42, v42
	v_exp_f32_e32 v43, v43
	v_cvt_pk_bf16_f32 v228, v38, v39
	v_add_f32_e32 v42, 1.0, v42
	v_add_f32_e32 v43, 1.0, v43
	v_rcp_f32_e32 v42, v42
	v_rcp_f32_e32 v43, v43
	s_nop 0
	v_pk_mul_f32 v[40:41], v[40:41], v[42:43]
	s_nop 0
	v_cvt_pk_bf16_f32 v229, v40, v41
	v_mul_f32_e32 v38, 0x3d372713, v34
	v_mul_f32_e32 v39, 0x3d372713, v35
	v_mul_f32_e32 v38, v34, v38
	v_mul_f32_e32 v39, v35, v39
	v_fma_f32 v38, v34, v38, v34
	v_fma_f32 v39, v35, v39, v35
	v_mul_f32_e32 v38, 0xbfcc422a, v38
	v_mul_f32_e32 v39, 0xbfcc422a, v39
	v_mul_f32_e32 v38, 0x3fb8aa3b, v38
	v_mul_f32_e32 v39, 0x3fb8aa3b, v39
	v_exp_f32_e32 v38, v38
	v_exp_f32_e32 v39, v39
	v_add_f32_e32 v38, 1.0, v38
	v_add_f32_e32 v39, 1.0, v39
	v_rcp_f32_e32 v38, v38
	v_rcp_f32_e32 v39, v39
	s_nop 0
	v_pk_mul_f32 v[34:35], v[34:35], v[38:39]
	v_mul_f32_e32 v38, 0x3d372713, v36
	v_mul_f32_e32 v39, 0x3d372713, v37
	v_mul_f32_e32 v38, v36, v38
	v_mul_f32_e32 v39, v37, v39
	v_fma_f32 v38, v36, v38, v36
	v_fma_f32 v39, v37, v39, v37
	v_mul_f32_e32 v38, 0xbfcc422a, v38
	v_mul_f32_e32 v39, 0xbfcc422a, v39
	v_mul_f32_e32 v38, 0x3fb8aa3b, v38
	v_mul_f32_e32 v39, 0x3fb8aa3b, v39
	v_exp_f32_e32 v38, v38
	v_exp_f32_e32 v39, v39
	v_cvt_pk_bf16_f32 v230, v34, v35
	v_add_f32_e32 v38, 1.0, v38
	v_add_f32_e32 v39, 1.0, v39
	v_rcp_f32_e32 v38, v38
	v_rcp_f32_e32 v39, v39
	s_nop 0
	v_pk_mul_f32 v[36:37], v[36:37], v[38:39]
	s_nop 0
	v_cvt_pk_bf16_f32 v231, v36, v37
	s_nop 1
	v_permlane16_swap_b32_e32 v224, v226
	v_permlane16_swap_b32_e32 v225, v227
	v_permlane16_swap_b32_e32 v228, v230
	v_permlane16_swap_b32_e32 v229, v231
	v_lshl_add_u64 v[240:241], v[62:63], 0, v[244:245]
	global_store_dwordx4 v[240:241], v[224:227], off offset:256
	global_store_dwordx4 v[240:241], v[228:231], off offset:320
	v_mul_f32_e32 v34, 0x3d372713, v30
	v_mul_f32_e32 v35, 0x3d372713, v31
	v_mul_f32_e32 v34, v30, v34
	v_mul_f32_e32 v35, v31, v35
	v_fma_f32 v34, v30, v34, v30
	v_fma_f32 v35, v31, v35, v31
	v_mul_f32_e32 v34, 0xbfcc422a, v34
	v_mul_f32_e32 v35, 0xbfcc422a, v35
	v_mul_f32_e32 v34, 0x3fb8aa3b, v34
	v_mul_f32_e32 v35, 0x3fb8aa3b, v35
	v_exp_f32_e32 v34, v34
	v_exp_f32_e32 v35, v35
	v_add_f32_e32 v34, 1.0, v34
	v_add_f32_e32 v35, 1.0, v35
	v_rcp_f32_e32 v34, v34
	v_rcp_f32_e32 v35, v35
	s_nop 0
	v_pk_mul_f32 v[30:31], v[30:31], v[34:35]
	v_mul_f32_e32 v34, 0x3d372713, v32
	v_mul_f32_e32 v35, 0x3d372713, v33
	v_mul_f32_e32 v34, v32, v34
	v_mul_f32_e32 v35, v33, v35
	v_fma_f32 v34, v32, v34, v32
	v_fma_f32 v35, v33, v35, v33
	v_mul_f32_e32 v34, 0xbfcc422a, v34
	v_mul_f32_e32 v35, 0xbfcc422a, v35
	v_mul_f32_e32 v34, 0x3fb8aa3b, v34
	v_mul_f32_e32 v35, 0x3fb8aa3b, v35
	v_exp_f32_e32 v34, v34
	v_exp_f32_e32 v35, v35
	v_add_f32_e32 v34, 1.0, v34
	v_add_f32_e32 v35, 1.0, v35
	v_rcp_f32_e32 v34, v34
	v_rcp_f32_e32 v35, v35
	s_nop 0
	v_pk_mul_f32 v[32:33], v[32:33], v[34:35]
	s_nop 0
	v_cvt_pk_bf16_f32 v233, v32, v33
	v_add_co_u32_e32 v32, vcc, s0, v126
	v_cvt_pk_bf16_f32 v232, v30, v31
	s_nop 0
	v_addc_co_u32_e32 v33, vcc, 0, v127, vcc
	v_mul_f32_e32 v32, 0x3d372713, v26
	v_mul_f32_e32 v33, 0x3d372713, v27
	v_mul_f32_e32 v32, v26, v32
	v_mul_f32_e32 v33, v27, v33
	v_fma_f32 v32, v26, v32, v26
	v_fma_f32 v33, v27, v33, v27
	v_mul_f32_e32 v32, 0xbfcc422a, v32
	v_mul_f32_e32 v33, 0xbfcc422a, v33
	v_mul_f32_e32 v32, 0x3fb8aa3b, v32
	v_mul_f32_e32 v33, 0x3fb8aa3b, v33
	v_exp_f32_e32 v32, v32
	v_exp_f32_e32 v33, v33
	v_lshl_add_u64 v[30:31], v[126:127], 0, s[8:9]
	v_add_f32_e32 v32, 1.0, v32
	v_add_f32_e32 v33, 1.0, v33
	v_rcp_f32_e32 v32, v32
	v_rcp_f32_e32 v33, v33
	s_nop 0
	v_pk_mul_f32 v[26:27], v[26:27], v[32:33]
	v_mul_f32_e32 v32, 0x3d372713, v28
	v_mul_f32_e32 v33, 0x3d372713, v29
	v_mul_f32_e32 v32, v28, v32
	v_mul_f32_e32 v33, v29, v33
	v_fma_f32 v32, v28, v32, v28
	v_fma_f32 v33, v29, v33, v29
	v_mul_f32_e32 v32, 0xbfcc422a, v32
	v_mul_f32_e32 v33, 0xbfcc422a, v33
	v_mul_f32_e32 v32, 0x3fb8aa3b, v32
	v_mul_f32_e32 v33, 0x3fb8aa3b, v33
	v_exp_f32_e32 v32, v32
	v_exp_f32_e32 v33, v33
	v_cvt_pk_bf16_f32 v234, v26, v27
	v_add_f32_e32 v32, 1.0, v32
	v_add_f32_e32 v33, 1.0, v33
	v_rcp_f32_e32 v32, v32
	v_rcp_f32_e32 v33, v33
	s_nop 0
	v_pk_mul_f32 v[28:29], v[28:29], v[32:33]
	s_nop 0
	v_cvt_pk_bf16_f32 v235, v28, v29
	v_mul_f32_e32 v26, 0x3d372713, v22
	v_mul_f32_e32 v27, 0x3d372713, v23
	v_mul_f32_e32 v26, v22, v26
	v_mul_f32_e32 v27, v23, v27
	v_fma_f32 v26, v22, v26, v22
	v_fma_f32 v27, v23, v27, v23
	v_mul_f32_e32 v26, 0xbfcc422a, v26
	v_mul_f32_e32 v27, 0xbfcc422a, v27
	v_mul_f32_e32 v26, 0x3fb8aa3b, v26
	v_mul_f32_e32 v27, 0x3fb8aa3b, v27
	v_exp_f32_e32 v26, v26
	v_exp_f32_e32 v27, v27
	v_add_f32_e32 v26, 1.0, v26
	v_add_f32_e32 v27, 1.0, v27
	v_rcp_f32_e32 v26, v26
	v_rcp_f32_e32 v27, v27
	s_nop 0
	v_pk_mul_f32 v[22:23], v[22:23], v[26:27]
	v_mul_f32_e32 v26, 0x3d372713, v24
	v_mul_f32_e32 v27, 0x3d372713, v25
	v_mul_f32_e32 v26, v24, v26
	v_mul_f32_e32 v27, v25, v27
	v_fma_f32 v26, v24, v26, v24
	v_fma_f32 v27, v25, v27, v25
	v_mul_f32_e32 v26, 0xbfcc422a, v26
	v_mul_f32_e32 v27, 0xbfcc422a, v27
	v_mul_f32_e32 v26, 0x3fb8aa3b, v26
	v_mul_f32_e32 v27, 0x3fb8aa3b, v27
	v_exp_f32_e32 v26, v26
	v_exp_f32_e32 v27, v27
	v_cvt_pk_bf16_f32 v236, v22, v23
	v_add_f32_e32 v26, 1.0, v26
	v_add_f32_e32 v27, 1.0, v27
	v_rcp_f32_e32 v26, v26
	v_rcp_f32_e32 v27, v27
	s_nop 0
	v_pk_mul_f32 v[24:25], v[24:25], v[26:27]
	s_nop 0
	v_cvt_pk_bf16_f32 v237, v24, v25
	v_mul_f32_e32 v22, 0x3d372713, v18
	v_mul_f32_e32 v23, 0x3d372713, v19
	v_mul_f32_e32 v22, v18, v22
	v_mul_f32_e32 v23, v19, v23
	v_fma_f32 v22, v18, v22, v18
	v_fma_f32 v23, v19, v23, v19
	v_mul_f32_e32 v22, 0xbfcc422a, v22
	v_mul_f32_e32 v23, 0xbfcc422a, v23
	v_mul_f32_e32 v22, 0x3fb8aa3b, v22
	v_mul_f32_e32 v23, 0x3fb8aa3b, v23
	v_exp_f32_e32 v22, v22
	v_exp_f32_e32 v23, v23
	v_add_f32_e32 v22, 1.0, v22
	v_add_f32_e32 v23, 1.0, v23
	v_rcp_f32_e32 v22, v22
	v_rcp_f32_e32 v23, v23
	s_nop 0
	v_pk_mul_f32 v[18:19], v[18:19], v[22:23]
	v_mul_f32_e32 v22, 0x3d372713, v20
	v_mul_f32_e32 v23, 0x3d372713, v21
	v_mul_f32_e32 v22, v20, v22
	v_mul_f32_e32 v23, v21, v23
	v_fma_f32 v22, v20, v22, v20
	v_fma_f32 v23, v21, v23, v21
	v_mul_f32_e32 v22, 0xbfcc422a, v22
	v_mul_f32_e32 v23, 0xbfcc422a, v23
	v_mul_f32_e32 v22, 0x3fb8aa3b, v22
	v_mul_f32_e32 v23, 0x3fb8aa3b, v23
	v_exp_f32_e32 v22, v22
	v_exp_f32_e32 v23, v23
	v_cvt_pk_bf16_f32 v238, v18, v19
	v_add_f32_e32 v22, 1.0, v22
	v_add_f32_e32 v23, 1.0, v23
	v_rcp_f32_e32 v22, v22
	v_rcp_f32_e32 v23, v23
	s_nop 0
	v_pk_mul_f32 v[20:21], v[20:21], v[22:23]
	s_nop 0
	v_cvt_pk_bf16_f32 v239, v20, v21
	s_nop 1
	v_permlane16_swap_b32_e32 v232, v234
	v_permlane16_swap_b32_e32 v233, v235
	v_permlane16_swap_b32_e32 v236, v238
	v_permlane16_swap_b32_e32 v237, v239
	v_lshl_add_u64 v[240:241], v[30:31], 0, v[244:245]
	global_store_dwordx4 v[240:241], v[232:235], off
	global_store_dwordx4 v[240:241], v[236:239], off offset:64
	v_mul_f32_e32 v18, 0x3d372713, v14
	v_mul_f32_e32 v19, 0x3d372713, v15
	v_mul_f32_e32 v18, v14, v18
	v_mul_f32_e32 v19, v15, v19
	v_fma_f32 v18, v14, v18, v14
	v_fma_f32 v19, v15, v19, v15
	v_mul_f32_e32 v18, 0xbfcc422a, v18
	v_mul_f32_e32 v19, 0xbfcc422a, v19
	v_mul_f32_e32 v18, 0x3fb8aa3b, v18
	v_mul_f32_e32 v19, 0x3fb8aa3b, v19
	v_exp_f32_e32 v18, v18
	v_exp_f32_e32 v19, v19
	v_add_f32_e32 v18, 1.0, v18
	v_add_f32_e32 v19, 1.0, v19
	v_rcp_f32_e32 v18, v18
	v_rcp_f32_e32 v19, v19
	s_nop 0
	v_pk_mul_f32 v[14:15], v[14:15], v[18:19]
	v_mul_f32_e32 v18, 0x3d372713, v16
	v_mul_f32_e32 v19, 0x3d372713, v17
	v_mul_f32_e32 v18, v16, v18
	v_mul_f32_e32 v19, v17, v19
	v_fma_f32 v18, v16, v18, v16
	v_fma_f32 v19, v17, v19, v17
	v_mul_f32_e32 v18, 0xbfcc422a, v18
	v_mul_f32_e32 v19, 0xbfcc422a, v19
	v_mul_f32_e32 v18, 0x3fb8aa3b, v18
	v_mul_f32_e32 v19, 0x3fb8aa3b, v19
	v_exp_f32_e32 v18, v18
	v_exp_f32_e32 v19, v19
	v_cvt_pk_bf16_f32 v178, v14, v15
	v_add_f32_e32 v18, 1.0, v18
	v_add_f32_e32 v19, 1.0, v19
	v_rcp_f32_e32 v18, v18
	v_rcp_f32_e32 v19, v19
	s_nop 0
	v_pk_mul_f32 v[16:17], v[16:17], v[18:19]
	s_nop 0
	v_cvt_pk_bf16_f32 v179, v16, v17
	v_mul_f32_e32 v14, 0x3d372713, v10
	v_mul_f32_e32 v15, 0x3d372713, v11
	v_mul_f32_e32 v14, v10, v14
	v_mul_f32_e32 v15, v11, v15
	v_fma_f32 v14, v10, v14, v10
	v_fma_f32 v15, v11, v15, v11
	v_mul_f32_e32 v14, 0xbfcc422a, v14
	v_mul_f32_e32 v15, 0xbfcc422a, v15
	v_mul_f32_e32 v14, 0x3fb8aa3b, v14
	v_mul_f32_e32 v15, 0x3fb8aa3b, v15
	v_exp_f32_e32 v14, v14
	v_exp_f32_e32 v15, v15
	v_add_f32_e32 v14, 1.0, v14
	v_add_f32_e32 v15, 1.0, v15
	v_rcp_f32_e32 v14, v14
	v_rcp_f32_e32 v15, v15
	s_nop 0
	v_pk_mul_f32 v[10:11], v[10:11], v[14:15]
	v_mul_f32_e32 v14, 0x3d372713, v12
	v_mul_f32_e32 v15, 0x3d372713, v13
	v_mul_f32_e32 v14, v12, v14
	v_mul_f32_e32 v15, v13, v15
	v_fma_f32 v14, v12, v14, v12
	v_fma_f32 v15, v13, v15, v13
	v_mul_f32_e32 v14, 0xbfcc422a, v14
	v_mul_f32_e32 v15, 0xbfcc422a, v15
	v_mul_f32_e32 v14, 0x3fb8aa3b, v14
	v_mul_f32_e32 v15, 0x3fb8aa3b, v15
	v_exp_f32_e32 v14, v14
	v_exp_f32_e32 v15, v15
	v_cvt_pk_bf16_f32 v180, v10, v11
	v_add_f32_e32 v14, 1.0, v14
	v_add_f32_e32 v15, 1.0, v15
	v_rcp_f32_e32 v14, v14
	v_rcp_f32_e32 v15, v15
	s_nop 0
	v_pk_mul_f32 v[12:13], v[12:13], v[14:15]
	s_nop 0
	v_cvt_pk_bf16_f32 v181, v12, v13
	v_mul_f32_e32 v10, 0x3d372713, v6
	v_mul_f32_e32 v11, 0x3d372713, v7
	v_mul_f32_e32 v10, v6, v10
	v_mul_f32_e32 v11, v7, v11
	v_fma_f32 v10, v6, v10, v6
	v_fma_f32 v11, v7, v11, v7
	v_mul_f32_e32 v10, 0xbfcc422a, v10
	v_mul_f32_e32 v11, 0xbfcc422a, v11
	v_mul_f32_e32 v10, 0x3fb8aa3b, v10
	v_mul_f32_e32 v11, 0x3fb8aa3b, v11
	v_exp_f32_e32 v10, v10
	v_exp_f32_e32 v11, v11
	v_add_f32_e32 v10, 1.0, v10
	v_add_f32_e32 v11, 1.0, v11
	v_rcp_f32_e32 v10, v10
	v_rcp_f32_e32 v11, v11
	s_nop 0
	v_pk_mul_f32 v[6:7], v[6:7], v[10:11]
	v_mul_f32_e32 v10, 0x3d372713, v8
	v_mul_f32_e32 v11, 0x3d372713, v9
	v_mul_f32_e32 v10, v8, v10
	v_mul_f32_e32 v11, v9, v11
	v_fma_f32 v10, v8, v10, v8
	v_fma_f32 v11, v9, v11, v9
	v_mul_f32_e32 v10, 0xbfcc422a, v10
	v_mul_f32_e32 v11, 0xbfcc422a, v11
	v_mul_f32_e32 v10, 0x3fb8aa3b, v10
	v_mul_f32_e32 v11, 0x3fb8aa3b, v11
	v_exp_f32_e32 v10, v10
	v_exp_f32_e32 v11, v11
	v_cvt_pk_bf16_f32 v182, v6, v7
	v_add_f32_e32 v10, 1.0, v10
	v_add_f32_e32 v11, 1.0, v11
	v_rcp_f32_e32 v10, v10
	v_rcp_f32_e32 v11, v11
	s_nop 0
	v_pk_mul_f32 v[8:9], v[8:9], v[10:11]
	s_nop 0
	v_cvt_pk_bf16_f32 v183, v8, v9
	v_mul_f32_e32 v6, 0x3d372713, v2
	v_mul_f32_e32 v7, 0x3d372713, v3
	v_mul_f32_e32 v6, v2, v6
	v_mul_f32_e32 v7, v3, v7
	v_fma_f32 v6, v2, v6, v2
	v_fma_f32 v7, v3, v7, v3
	v_mul_f32_e32 v6, 0xbfcc422a, v6
	v_mul_f32_e32 v7, 0xbfcc422a, v7
	v_mul_f32_e32 v6, 0x3fb8aa3b, v6
	v_mul_f32_e32 v7, 0x3fb8aa3b, v7
	v_exp_f32_e32 v6, v6
	v_exp_f32_e32 v7, v7
	v_add_f32_e32 v6, 1.0, v6
	v_add_f32_e32 v7, 1.0, v7
	v_rcp_f32_e32 v6, v6
	v_rcp_f32_e32 v7, v7
	s_nop 0
	v_pk_mul_f32 v[2:3], v[2:3], v[6:7]
	v_mul_f32_e32 v6, 0x3d372713, v4
	v_mul_f32_e32 v7, 0x3d372713, v5
	v_mul_f32_e32 v6, v4, v6
	v_mul_f32_e32 v7, v5, v7
	v_fma_f32 v6, v4, v6, v4
	v_fma_f32 v7, v5, v7, v5
	v_mul_f32_e32 v6, 0xbfcc422a, v6
	v_mul_f32_e32 v7, 0xbfcc422a, v7
	v_mul_f32_e32 v6, 0x3fb8aa3b, v6
	v_mul_f32_e32 v7, 0x3fb8aa3b, v7
	v_exp_f32_e32 v6, v6
	v_exp_f32_e32 v7, v7
	v_cvt_pk_bf16_f32 v184, v2, v3
	v_add_f32_e32 v6, 1.0, v6
	v_add_f32_e32 v7, 1.0, v7
	v_rcp_f32_e32 v6, v6
	v_rcp_f32_e32 v7, v7
	s_nop 0
	v_pk_mul_f32 v[4:5], v[4:5], v[6:7]
	s_nop 0
	v_cvt_pk_bf16_f32 v185, v4, v5
	s_nop 1
	v_permlane16_swap_b32_e32 v178, v180
	v_permlane16_swap_b32_e32 v179, v181
	v_permlane16_swap_b32_e32 v182, v184
	v_permlane16_swap_b32_e32 v183, v185
	v_lshl_add_u64 v[240:241], v[30:31], 0, v[244:245]
	global_store_dwordx4 v[240:241], v[178:181], off offset:256
	global_store_dwordx4 v[240:241], v[182:185], off offset:320

.LBB0_341:
	s_or_b64 exec, exec, s[40:41]
	v_mbcnt_lo_u32_b32 v244, -1, 0
	v_mbcnt_hi_u32_b32 v244, -1, v244
	v_bfe_u32 v244, v244, 4, 1
	v_mul_u32_u24_e32 v244, 24, v244
	v_mov_b32_e32 v245, 0
	v_lshl_or_b32 v132, s36, 7, v143
	v_mov_b32_e32 v130, v142
	s_andn2_b64 vcc, exec, s[38:39]
	v_lshl_add_u32 v140, v130, 2, v154
	ds_read2_b32 v[134:135], v140 offset1:16
	v_ashrrev_i32_e32 v133, 31, v132
	v_lshl_add_u32 v130, s34, 8, v130
	s_waitcnt lgkmcnt(0)
	v_pk_mul_f32 v[122:123], v[122:123], v[134:135] op_sel_hi:[1,0]
	s_nop 0
	v_mul_f32_e32 v136, 0xbfb8aa3b, v122
	v_mul_f32_e32 v137, 0xbfb8aa3b, v123
	v_pk_mul_f32 v[124:125], v[124:125], v[134:135] op_sel_hi:[1,0]
	v_exp_f32_e32 v136, v136
	v_exp_f32_e32 v137, v137
	v_mul_f32_e32 v138, 0xbfb8aa3b, v124
	v_mul_f32_e32 v139, 0xbfb8aa3b, v125
	v_exp_f32_e32 v138, v138
	v_exp_f32_e32 v139, v139
	v_add_f32_e32 v136, 1.0, v136
	v_add_f32_e32 v137, 1.0, v137
	v_rcp_f32_e32 v136, v136
	v_rcp_f32_e32 v137, v137
	v_add_f32_e32 v138, 1.0, v138
	v_add_f32_e32 v139, 1.0, v139
	v_rcp_f32_e32 v138, v138
	v_rcp_f32_e32 v139, v139
	v_pk_mul_f32 v[122:123], v[122:123], v[136:137]
	v_pk_mul_f32 v[126:127], v[126:127], v[134:135] op_sel_hi:[1,0]
	v_pk_mul_f32 v[114:115], v[114:115], v[134:135] op_sel_hi:[1,0]
	v_pk_mul_f32 v[122:123], v[126:127], v[122:123]
	v_pk_mul_f32 v[124:125], v[124:125], v[138:139]
	v_pk_mul_f32 v[126:127], v[128:129], v[134:135] op_sel_hi:[1,0]
	v_pk_mul_f32 v[116:117], v[116:117], v[134:135] op_sel_hi:[1,0]
	v_pk_mul_f32 v[124:125], v[126:127], v[124:125]
	v_cvt_pk_bf16_f32 v224, v122, v123
	v_cvt_pk_bf16_f32 v225, v124, v125
	v_lshlrev_b64 v[124:125], 1, v[132:133]
	v_mul_f32_e32 v132, 0xbfb8aa3b, v114
	v_mul_f32_e32 v133, 0xbfb8aa3b, v115
	v_exp_f32_e32 v132, v132
	v_exp_f32_e32 v133, v133
	v_mov_b64_e32 v[122:123], s[14:15]
	v_mad_i64_i32 v[128:129], s[0:1], v130, s53, v[122:123]
	v_lshl_add_u64 v[128:129], v[128:129], 0, v[124:125]
	v_add_f32_e32 v126, 1.0, v132
	v_add_f32_e32 v127, 1.0, v133
	v_mul_f32_e32 v132, 0xbfb8aa3b, v116
	v_mul_f32_e32 v133, 0xbfb8aa3b, v117
	v_exp_f32_e32 v132, v132
	v_exp_f32_e32 v133, v133
	v_rcp_f32_e32 v126, v126
	v_rcp_f32_e32 v127, v127
	v_add_f32_e32 v132, 1.0, v132
	v_add_f32_e32 v133, 1.0, v133
	v_rcp_f32_e32 v132, v132
	v_rcp_f32_e32 v133, v133
	v_pk_mul_f32 v[114:115], v[114:115], v[126:127]
	v_pk_mul_f32 v[118:119], v[118:119], v[134:135] op_sel_hi:[1,0]
	v_pk_mul_f32 v[106:107], v[106:107], v[134:135] op_sel_hi:[1,0]
	v_pk_mul_f32 v[114:115], v[118:119], v[114:115]
	v_pk_mul_f32 v[116:117], v[116:117], v[132:133]
	v_pk_mul_f32 v[118:119], v[120:121], v[134:135] op_sel_hi:[1,0]
	v_cvt_pk_bf16_f32 v226, v114, v115
	v_pk_mul_f32 v[116:117], v[118:119], v[116:117]
	v_pk_mul_f32 v[108:109], v[108:109], v[134:135] op_sel_hi:[1,0]
	v_cvt_pk_bf16_f32 v227, v116, v117
	v_mul_f32_e32 v116, 0xbfb8aa3b, v106
	v_mul_f32_e32 v117, 0xbfb8aa3b, v107
	v_exp_f32_e32 v116, v116
	v_exp_f32_e32 v117, v117
	v_pk_mul_f32 v[110:111], v[110:111], v[134:135] op_sel_hi:[1,0]
	v_add_f32_e32 v114, 1.0, v116
	v_add_f32_e32 v115, 1.0, v117
	v_mul_f32_e32 v116, 0xbfb8aa3b, v108
	v_mul_f32_e32 v117, 0xbfb8aa3b, v109
	v_exp_f32_e32 v116, v116
	v_exp_f32_e32 v117, v117
	v_rcp_f32_e32 v114, v114
	v_rcp_f32_e32 v115, v115
	v_add_f32_e32 v116, 1.0, v116
	v_add_f32_e32 v117, 1.0, v117
	v_rcp_f32_e32 v116, v116
	v_rcp_f32_e32 v117, v117
	v_pk_mul_f32 v[106:107], v[106:107], v[114:115]
	v_pk_mul_f32 v[98:99], v[98:99], v[134:135] op_sel_hi:[1,0]
	v_pk_mul_f32 v[106:107], v[110:111], v[106:107]
	v_pk_mul_f32 v[108:109], v[108:109], v[116:117]
	v_pk_mul_f32 v[110:111], v[112:113], v[134:135] op_sel_hi:[1,0]
	v_cvt_pk_bf16_f32 v228, v106, v107
	v_pk_mul_f32 v[108:109], v[110:111], v[108:109]
	v_pk_mul_f32 v[100:101], v[100:101], v[134:135] op_sel_hi:[1,0]
	v_cvt_pk_bf16_f32 v229, v108, v109
	v_mul_f32_e32 v108, 0xbfb8aa3b, v98
	v_mul_f32_e32 v109, 0xbfb8aa3b, v99
	v_exp_f32_e32 v108, v108
	v_exp_f32_e32 v109, v109
	v_pk_mul_f32 v[102:103], v[102:103], v[134:135] op_sel_hi:[1,0]
	v_add_f32_e32 v106, 1.0, v108
	v_add_f32_e32 v107, 1.0, v109
	v_mul_f32_e32 v108, 0xbfb8aa3b, v100
	v_mul_f32_e32 v109, 0xbfb8aa3b, v101
	v_exp_f32_e32 v108, v108
	v_exp_f32_e32 v109, v109
	v_rcp_f32_e32 v106, v106
	v_rcp_f32_e32 v107, v107
	v_add_f32_e32 v108, 1.0, v108
	v_add_f32_e32 v109, 1.0, v109
	v_rcp_f32_e32 v108, v108
	v_rcp_f32_e32 v109, v109
	v_pk_mul_f32 v[98:99], v[98:99], v[106:107]
	v_pk_mul_f32 v[100:101], v[100:101], v[108:109]
	v_pk_mul_f32 v[98:99], v[102:103], v[98:99]
	v_pk_mul_f32 v[102:103], v[104:105], v[134:135] op_sel_hi:[1,0]
	v_cvt_pk_bf16_f32 v230, v98, v99
	v_pk_mul_f32 v[100:101], v[102:103], v[100:101]
	v_add_u32_e32 v104, 16, v130
	v_cvt_pk_bf16_f32 v231, v100, v101
	s_nop 1
	v_permlane16_swap_b32_e32 v224, v226
	v_permlane16_swap_b32_e32 v225, v227
	v_permlane16_swap_b32_e32 v228, v230
	v_permlane16_swap_b32_e32 v229, v231
	v_lshl_add_u64 v[240:241], v[128:129], 0, v[244:245]
	global_store_dwordx4 v[240:241], v[224:227], off
	global_store_dwordx4 v[240:241], v[228:231], off offset:64
	v_mov_b32_e32 v98, v135
	v_pk_mul_f32 v[90:91], v[90:91], v[98:99] op_sel_hi:[1,0]
	s_nop 0
	v_mul_f32_e32 v99, 0xbfb8aa3b, v90
	v_exp_f32_e32 v99, v99
	v_mul_f32_e32 v100, 0xbfb8aa3b, v91
	v_exp_f32_e32 v101, v100
	v_add_f32_e32 v99, 1.0, v99
	v_rcp_f32_e32 v100, v99
	v_add_f32_e32 v99, 1.0, v101
	v_pk_mul_f32 v[92:93], v[92:93], v[98:99] op_sel_hi:[1,0]
	s_nop 0
	v_mul_f32_e32 v101, 0xbfb8aa3b, v92
	v_exp_f32_e32 v102, v101
	v_mul_f32_e32 v101, 0xbfb8aa3b, v93
	v_exp_f32_e32 v103, v101
	v_rcp_f32_e32 v101, v99
	v_add_f32_e32 v99, 1.0, v102
	v_rcp_f32_e32 v102, v99
	v_add_f32_e32 v99, 1.0, v103
	v_rcp_f32_e32 v103, v99
	v_pk_mul_f32 v[90:91], v[90:91], v[100:101]
	v_pk_mul_f32 v[94:95], v[94:95], v[98:99] op_sel_hi:[1,0]
	v_pk_mul_f32 v[82:83], v[82:83], v[98:99] op_sel_hi:[1,0]
	v_pk_mul_f32 v[90:91], v[94:95], v[90:91]
	v_pk_mul_f32 v[92:93], v[92:93], v[102:103]
	v_pk_mul_f32 v[94:95], v[96:97], v[98:99] op_sel_hi:[1,0]
	v_cvt_pk_bf16_f32 v232, v90, v91
	v_pk_mul_f32 v[92:93], v[94:95], v[92:93]
	v_mul_f32_e32 v94, 0xbfb8aa3b, v82
	v_mul_f32_e32 v95, 0xbfb8aa3b, v83
	v_exp_f32_e32 v94, v94
	v_exp_f32_e32 v95, v95
	v_cvt_pk_bf16_f32 v233, v92, v93
	v_mad_i64_i32 v[92:93], s[0:1], v104, s53, v[122:123]
	v_lshl_add_u64 v[92:93], v[92:93], 0, v[124:125]
	v_pk_mul_f32 v[84:85], v[84:85], v[98:99] op_sel_hi:[1,0]
	v_add_f32_e32 v90, 1.0, v94
	v_add_f32_e32 v91, 1.0, v95
	v_mul_f32_e32 v94, 0xbfb8aa3b, v84
	v_mul_f32_e32 v95, 0xbfb8aa3b, v85
	v_exp_f32_e32 v94, v94
	v_exp_f32_e32 v95, v95
	v_rcp_f32_e32 v90, v90
	v_rcp_f32_e32 v91, v91
	v_add_f32_e32 v94, 1.0, v94
	v_add_f32_e32 v95, 1.0, v95
	v_rcp_f32_e32 v94, v94
	v_rcp_f32_e32 v95, v95
	v_pk_mul_f32 v[82:83], v[82:83], v[90:91]
	v_pk_mul_f32 v[86:87], v[86:87], v[98:99] op_sel_hi:[1,0]
	v_pk_mul_f32 v[74:75], v[74:75], v[98:99] op_sel_hi:[1,0]
	v_pk_mul_f32 v[82:83], v[86:87], v[82:83]
	v_pk_mul_f32 v[84:85], v[84:85], v[94:95]
	v_pk_mul_f32 v[86:87], v[88:89], v[98:99] op_sel_hi:[1,0]
	v_cvt_pk_bf16_f32 v234, v82, v83
	v_pk_mul_f32 v[84:85], v[86:87], v[84:85]
	v_pk_mul_f32 v[76:77], v[76:77], v[98:99] op_sel_hi:[1,0]
	v_cvt_pk_bf16_f32 v235, v84, v85
	v_mul_f32_e32 v84, 0xbfb8aa3b, v74
	v_mul_f32_e32 v85, 0xbfb8aa3b, v75
	v_exp_f32_e32 v84, v84
	v_exp_f32_e32 v85, v85
	v_pk_mul_f32 v[78:79], v[78:79], v[98:99] op_sel_hi:[1,0]
	v_add_f32_e32 v82, 1.0, v84
	v_add_f32_e32 v83, 1.0, v85
	v_mul_f32_e32 v84, 0xbfb8aa3b, v76
	v_mul_f32_e32 v85, 0xbfb8aa3b, v77
	v_exp_f32_e32 v84, v84
	v_exp_f32_e32 v85, v85
	v_rcp_f32_e32 v82, v82
	v_rcp_f32_e32 v83, v83
	v_add_f32_e32 v84, 1.0, v84
	v_add_f32_e32 v85, 1.0, v85
	v_rcp_f32_e32 v84, v84
	v_rcp_f32_e32 v85, v85
	v_pk_mul_f32 v[74:75], v[74:75], v[82:83]
	v_pk_mul_f32 v[66:67], v[66:67], v[98:99] op_sel_hi:[1,0]
	v_pk_mul_f32 v[74:75], v[78:79], v[74:75]
	v_pk_mul_f32 v[76:77], v[76:77], v[84:85]
	v_pk_mul_f32 v[78:79], v[80:81], v[98:99] op_sel_hi:[1,0]
	v_cvt_pk_bf16_f32 v236, v74, v75
	v_pk_mul_f32 v[76:77], v[78:79], v[76:77]
	v_pk_mul_f32 v[68:69], v[68:69], v[98:99] op_sel_hi:[1,0]
	v_cvt_pk_bf16_f32 v237, v76, v77
	v_mul_f32_e32 v76, 0xbfb8aa3b, v66
	v_mul_f32_e32 v77, 0xbfb8aa3b, v67
	v_exp_f32_e32 v76, v76
	v_exp_f32_e32 v77, v77
	v_pk_mul_f32 v[70:71], v[70:71], v[98:99] op_sel_hi:[1,0]
	v_add_f32_e32 v74, 1.0, v76
	v_add_f32_e32 v75, 1.0, v77
	v_mul_f32_e32 v76, 0xbfb8aa3b, v68
	v_mul_f32_e32 v77, 0xbfb8aa3b, v69
	v_exp_f32_e32 v76, v76
	v_exp_f32_e32 v77, v77
	v_rcp_f32_e32 v74, v74
	v_rcp_f32_e32 v75, v75
	v_add_f32_e32 v76, 1.0, v76
	v_add_f32_e32 v77, 1.0, v77
	v_rcp_f32_e32 v76, v76
	v_rcp_f32_e32 v77, v77
	v_pk_mul_f32 v[66:67], v[66:67], v[74:75]
	v_pk_mul_f32 v[68:69], v[68:69], v[76:77]
	v_pk_mul_f32 v[66:67], v[70:71], v[66:67]
	v_pk_mul_f32 v[70:71], v[72:73], v[98:99] op_sel_hi:[1,0]
	ds_read2_b32 v[72:73], v140 offset0:128 offset1:144
	v_pk_mul_f32 v[68:69], v[70:71], v[68:69]
	v_cvt_pk_bf16_f32 v238, v66, v67
	v_cvt_pk_bf16_f32 v239, v68, v69
	s_nop 1
	v_permlane16_swap_b32_e32 v232, v234
	v_permlane16_swap_b32_e32 v233, v235
	v_permlane16_swap_b32_e32 v236, v238
	v_permlane16_swap_b32_e32 v237, v239
	v_lshl_add_u64 v[240:241], v[92:93], 0, v[244:245]
	global_store_dwordx4 v[240:241], v[232:235], off
	global_store_dwordx4 v[240:241], v[236:239], off offset:64
	s_waitcnt lgkmcnt(0)
	v_pk_mul_f32 v[58:59], v[58:59], v[72:73] op_sel_hi:[1,0]
	v_pk_mul_f32 v[60:61], v[60:61], v[72:73] op_sel_hi:[1,0]
	v_mul_f32_e32 v66, 0xbfb8aa3b, v58
	v_mul_f32_e32 v67, 0xbfb8aa3b, v59
	v_exp_f32_e32 v66, v66
	v_exp_f32_e32 v67, v67
	v_mul_f32_e32 v68, 0xbfb8aa3b, v60
	v_mul_f32_e32 v69, 0xbfb8aa3b, v61
	v_exp_f32_e32 v68, v68
	v_exp_f32_e32 v69, v69
	v_add_f32_e32 v66, 1.0, v66
	v_add_f32_e32 v67, 1.0, v67
	v_rcp_f32_e32 v66, v66
	v_rcp_f32_e32 v67, v67
	v_add_f32_e32 v68, 1.0, v68
	v_add_f32_e32 v69, 1.0, v69
	v_rcp_f32_e32 v68, v68
	v_rcp_f32_e32 v69, v69
	v_pk_mul_f32 v[58:59], v[58:59], v[66:67]
	v_pk_mul_f32 v[62:63], v[62:63], v[72:73] op_sel_hi:[1,0]
	v_pk_mul_f32 v[50:51], v[50:51], v[72:73] op_sel_hi:[1,0]
	v_pk_mul_f32 v[58:59], v[62:63], v[58:59]
	v_pk_mul_f32 v[60:61], v[60:61], v[68:69]
	v_pk_mul_f32 v[62:63], v[64:65], v[72:73] op_sel_hi:[1,0]
	v_add_u32_e32 v70, 0x80, v130
	v_pk_mul_f32 v[60:61], v[62:63], v[60:61]
	v_mul_f32_e32 v62, 0xbfb8aa3b, v50
	v_mul_f32_e32 v63, 0xbfb8aa3b, v51
	v_exp_f32_e32 v62, v62
	v_exp_f32_e32 v63, v63
	v_cvt_pk_bf16_f32 v224, v58, v59
	v_cvt_pk_bf16_f32 v225, v60, v61
	v_mad_i64_i32 v[60:61], s[0:1], v70, s53, v[122:123]
	v_lshl_add_u64 v[60:61], v[60:61], 0, v[124:125]
	v_pk_mul_f32 v[52:53], v[52:53], v[72:73] op_sel_hi:[1,0]
	v_add_f32_e32 v58, 1.0, v62
	v_add_f32_e32 v59, 1.0, v63
	v_mul_f32_e32 v62, 0xbfb8aa3b, v52
	v_mul_f32_e32 v63, 0xbfb8aa3b, v53
	v_exp_f32_e32 v62, v62
	v_exp_f32_e32 v63, v63
	v_rcp_f32_e32 v58, v58
	v_rcp_f32_e32 v59, v59
	v_add_f32_e32 v62, 1.0, v62
	v_add_f32_e32 v63, 1.0, v63
	v_rcp_f32_e32 v62, v62
	v_rcp_f32_e32 v63, v63
	v_pk_mul_f32 v[50:51], v[50:51], v[58:59]
	v_pk_mul_f32 v[54:55], v[54:55], v[72:73] op_sel_hi:[1,0]
	v_pk_mul_f32 v[42:43], v[42:43], v[72:73] op_sel_hi:[1,0]
	v_pk_mul_f32 v[50:51], v[54:55], v[50:51]
	v_pk_mul_f32 v[52:53], v[52:53], v[62:63]
	v_pk_mul_f32 v[54:55], v[56:57], v[72:73] op_sel_hi:[1,0]
	v_cvt_pk_bf16_f32 v226, v50, v51
	v_pk_mul_f32 v[52:53], v[54:55], v[52:53]
	v_pk_mul_f32 v[44:45], v[44:45], v[72:73] op_sel_hi:[1,0]
	v_cvt_pk_bf16_f32 v227, v52, v53
	v_mul_f32_e32 v52, 0xbfb8aa3b, v42
	v_mul_f32_e32 v53, 0xbfb8aa3b, v43
	v_exp_f32_e32 v52, v52
	v_exp_f32_e32 v53, v53
	v_pk_mul_f32 v[46:47], v[46:47], v[72:73] op_sel_hi:[1,0]
	v_add_f32_e32 v50, 1.0, v52
	v_add_f32_e32 v51, 1.0, v53
	v_mul_f32_e32 v52, 0xbfb8aa3b, v44
	v_mul_f32_e32 v53, 0xbfb8aa3b, v45
	v_exp_f32_e32 v52, v52
	v_exp_f32_e32 v53, v53
	v_rcp_f32_e32 v50, v50
	v_rcp_f32_e32 v51, v51
	v_add_f32_e32 v52, 1.0, v52
	v_add_f32_e32 v53, 1.0, v53
	v_rcp_f32_e32 v52, v52
	v_rcp_f32_e32 v53, v53
	v_pk_mul_f32 v[42:43], v[42:43], v[50:51]
	v_pk_mul_f32 v[34:35], v[34:35], v[72:73] op_sel_hi:[1,0]
	v_pk_mul_f32 v[42:43], v[46:47], v[42:43]
	v_pk_mul_f32 v[44:45], v[44:45], v[52:53]
	v_pk_mul_f32 v[46:47], v[48:49], v[72:73] op_sel_hi:[1,0]
	v_cvt_pk_bf16_f32 v228, v42, v43
	v_pk_mul_f32 v[44:45], v[46:47], v[44:45]
	v_pk_mul_f32 v[36:37], v[36:37], v[72:73] op_sel_hi:[1,0]
	v_cvt_pk_bf16_f32 v229, v44, v45
	v_mul_f32_e32 v44, 0xbfb8aa3b, v34
	v_mul_f32_e32 v45, 0xbfb8aa3b, v35
	v_exp_f32_e32 v44, v44
	v_exp_f32_e32 v45, v45
	v_pk_mul_f32 v[38:39], v[38:39], v[72:73] op_sel_hi:[1,0]
	v_add_f32_e32 v42, 1.0, v44
	v_add_f32_e32 v43, 1.0, v45
	v_mul_f32_e32 v44, 0xbfb8aa3b, v36
	v_mul_f32_e32 v45, 0xbfb8aa3b, v37
	v_exp_f32_e32 v44, v44
	v_exp_f32_e32 v45, v45
	v_rcp_f32_e32 v42, v42
	v_rcp_f32_e32 v43, v43
	v_add_f32_e32 v44, 1.0, v44
	v_add_f32_e32 v45, 1.0, v45
	v_rcp_f32_e32 v44, v44
	v_rcp_f32_e32 v45, v45
	v_pk_mul_f32 v[34:35], v[34:35], v[42:43]
	v_pk_mul_f32 v[36:37], v[36:37], v[44:45]
	v_pk_mul_f32 v[34:35], v[38:39], v[34:35]
	v_pk_mul_f32 v[38:39], v[40:41], v[72:73] op_sel_hi:[1,0]
	v_cvt_pk_bf16_f32 v230, v34, v35
	v_pk_mul_f32 v[36:37], v[38:39], v[36:37]
	v_add_u32_e32 v40, 0x90, v130
	v_cvt_pk_bf16_f32 v231, v36, v37
	s_nop 1
	v_permlane16_swap_b32_e32 v224, v226
	v_permlane16_swap_b32_e32 v225, v227
	v_permlane16_swap_b32_e32 v228, v230
	v_permlane16_swap_b32_e32 v229, v231
	v_lshl_add_u64 v[240:241], v[60:61], 0, v[244:245]
	global_store_dwordx4 v[240:241], v[224:227], off
	global_store_dwordx4 v[240:241], v[228:231], off offset:64
	v_mov_b32_e32 v34, v73
	v_pk_mul_f32 v[26:27], v[26:27], v[34:35] op_sel_hi:[1,0]
	s_nop 0
	v_mul_f32_e32 v35, 0xbfb8aa3b, v26
	v_exp_f32_e32 v35, v35
	v_mul_f32_e32 v36, 0xbfb8aa3b, v27
	v_exp_f32_e32 v37, v36
	v_add_f32_e32 v35, 1.0, v35
	v_rcp_f32_e32 v36, v35
	v_add_f32_e32 v35, 1.0, v37
	v_pk_mul_f32 v[28:29], v[28:29], v[34:35] op_sel_hi:[1,0]
	s_nop 0
	v_mul_f32_e32 v37, 0xbfb8aa3b, v28
	v_exp_f32_e32 v38, v37
	v_mul_f32_e32 v37, 0xbfb8aa3b, v29
	v_exp_f32_e32 v39, v37
	v_rcp_f32_e32 v37, v35
	v_add_f32_e32 v35, 1.0, v38
	v_rcp_f32_e32 v38, v35
	v_add_f32_e32 v35, 1.0, v39
	v_rcp_f32_e32 v39, v35
	v_pk_mul_f32 v[26:27], v[26:27], v[36:37]
	v_pk_mul_f32 v[30:31], v[30:31], v[34:35] op_sel_hi:[1,0]
	v_pk_mul_f32 v[18:19], v[18:19], v[34:35] op_sel_hi:[1,0]
	v_pk_mul_f32 v[26:27], v[30:31], v[26:27]
	v_pk_mul_f32 v[28:29], v[28:29], v[38:39]
	v_pk_mul_f32 v[30:31], v[32:33], v[34:35] op_sel_hi:[1,0]
	v_cvt_pk_bf16_f32 v232, v26, v27
	v_pk_mul_f32 v[28:29], v[30:31], v[28:29]
	v_mul_f32_e32 v30, 0xbfb8aa3b, v18
	v_mul_f32_e32 v31, 0xbfb8aa3b, v19
	v_exp_f32_e32 v30, v30
	v_exp_f32_e32 v31, v31
	v_cvt_pk_bf16_f32 v233, v28, v29
	v_mad_i64_i32 v[28:29], s[0:1], v40, s53, v[122:123]
	v_lshl_add_u64 v[28:29], v[28:29], 0, v[124:125]
	v_pk_mul_f32 v[20:21], v[20:21], v[34:35] op_sel_hi:[1,0]
	v_add_f32_e32 v26, 1.0, v30
	v_add_f32_e32 v27, 1.0, v31
	v_mul_f32_e32 v30, 0xbfb8aa3b, v20
	v_mul_f32_e32 v31, 0xbfb8aa3b, v21
	v_exp_f32_e32 v30, v30
	v_exp_f32_e32 v31, v31
	v_rcp_f32_e32 v26, v26
	v_rcp_f32_e32 v27, v27
	v_add_f32_e32 v30, 1.0, v30
	v_add_f32_e32 v31, 1.0, v31
	v_rcp_f32_e32 v30, v30
	v_rcp_f32_e32 v31, v31
	v_pk_mul_f32 v[18:19], v[18:19], v[26:27]
	v_pk_mul_f32 v[22:23], v[22:23], v[34:35] op_sel_hi:[1,0]
	v_pk_mul_f32 v[10:11], v[10:11], v[34:35] op_sel_hi:[1,0]
	v_pk_mul_f32 v[18:19], v[22:23], v[18:19]
	v_pk_mul_f32 v[20:21], v[20:21], v[30:31]
	v_pk_mul_f32 v[22:23], v[24:25], v[34:35] op_sel_hi:[1,0]
	v_cvt_pk_bf16_f32 v234, v18, v19
	v_pk_mul_f32 v[20:21], v[22:23], v[20:21]
	v_pk_mul_f32 v[12:13], v[12:13], v[34:35] op_sel_hi:[1,0]
	v_cvt_pk_bf16_f32 v235, v20, v21
	v_mul_f32_e32 v20, 0xbfb8aa3b, v10
	v_mul_f32_e32 v21, 0xbfb8aa3b, v11
	v_exp_f32_e32 v20, v20
	v_exp_f32_e32 v21, v21
	v_pk_mul_f32 v[14:15], v[14:15], v[34:35] op_sel_hi:[1,0]
	v_add_f32_e32 v18, 1.0, v20
	v_add_f32_e32 v19, 1.0, v21
	v_mul_f32_e32 v20, 0xbfb8aa3b, v12
	v_mul_f32_e32 v21, 0xbfb8aa3b, v13
	v_exp_f32_e32 v20, v20
	v_exp_f32_e32 v21, v21
	v_rcp_f32_e32 v18, v18
	v_rcp_f32_e32 v19, v19
	v_add_f32_e32 v20, 1.0, v20
	v_add_f32_e32 v21, 1.0, v21
	v_rcp_f32_e32 v20, v20
	v_rcp_f32_e32 v21, v21
	v_pk_mul_f32 v[10:11], v[10:11], v[18:19]
	v_pk_mul_f32 v[2:3], v[2:3], v[34:35] op_sel_hi:[1,0]
	v_pk_mul_f32 v[10:11], v[14:15], v[10:11]
	v_pk_mul_f32 v[12:13], v[12:13], v[20:21]
	v_pk_mul_f32 v[14:15], v[16:17], v[34:35] op_sel_hi:[1,0]
	v_cvt_pk_bf16_f32 v236, v10, v11
	v_pk_mul_f32 v[12:13], v[14:15], v[12:13]
	v_pk_mul_f32 v[4:5], v[4:5], v[34:35] op_sel_hi:[1,0]
	v_cvt_pk_bf16_f32 v237, v12, v13
	v_mul_f32_e32 v12, 0xbfb8aa3b, v2
	v_mul_f32_e32 v13, 0xbfb8aa3b, v3
	v_exp_f32_e32 v12, v12
	v_exp_f32_e32 v13, v13
	v_pk_mul_f32 v[6:7], v[6:7], v[34:35] op_sel_hi:[1,0]
	v_add_f32_e32 v10, 1.0, v12
	v_add_f32_e32 v11, 1.0, v13
	v_mul_f32_e32 v12, 0xbfb8aa3b, v4
	v_mul_f32_e32 v13, 0xbfb8aa3b, v5
	v_exp_f32_e32 v12, v12
	v_exp_f32_e32 v13, v13
	v_rcp_f32_e32 v10, v10
	v_rcp_f32_e32 v11, v11
	v_add_f32_e32 v12, 1.0, v12
	v_add_f32_e32 v13, 1.0, v13
	v_rcp_f32_e32 v12, v12
	v_rcp_f32_e32 v13, v13
	v_pk_mul_f32 v[2:3], v[2:3], v[10:11]
	v_pk_mul_f32 v[4:5], v[4:5], v[12:13]
	v_pk_mul_f32 v[2:3], v[6:7], v[2:3]
	v_pk_mul_f32 v[6:7], v[8:9], v[34:35] op_sel_hi:[1,0]
	v_cvt_pk_bf16_f32 v238, v2, v3
	v_pk_mul_f32 v[4:5], v[6:7], v[4:5]
	s_nop 0
	v_cvt_pk_bf16_f32 v239, v4, v5
	s_nop 1
	v_permlane16_swap_b32_e32 v232, v234
	v_permlane16_swap_b32_e32 v233, v235
	v_permlane16_swap_b32_e32 v236, v238
	v_permlane16_swap_b32_e32 v237, v239
	v_lshl_add_u64 v[240:241], v[28:29], 0, v[244:245]
	global_store_dwordx4 v[240:241], v[232:235], off
	global_store_dwordx4 v[240:241], v[236:239], off offset:64
	s_barrier
	s_cbranch_vccz .LBB0_371
